# N=1024 GEMMs (D1/OUT/D2): 6th tile round (12 tiles on 12 blocks) replaced by hand-written 64x64 sub-tile pass on 192 blocks at phase start
# speedup vs baseline: 1.0452x; 1.0049x over previous
; #define LAS __attribute__((address_space(3)))
;     DI bool next(int i, Unit& u) const {
;         const long L = (long)i * G + c; if (L >= nwg) return false;
;         int wgid = (int)L; { const int q = nwg / NXCD, r = nwg % NXCD, xcd = wgid % NXCD, off = wgid / NXCD; wgid = (xcd < r ? xcd * (q + 1) : r * (q + 1) + (xcd - r) * q) + off; }
;         const int nig = WGM * nN, gid = wgid / nig, fm = gid * WGM, gsz = (nM - fm) < WGM ? (nM - fm) : WGM;
;         u.pm = fm + ((wgid % nig) % gsz); u.pn = (wgid % nig) / gsz; return true;
;     }
; template <class Epi>
; DI void gemm_phase(int wv, LAS unsigned char* lds, const Gemm g, const StaticOrder& S, const Epi& E) {
;     const int tid = tid_(wv), wid = __builtin_amdgcn_readfirstlane(tid >> 6), lane = tid & 63, wr = wid >> 2, wc = wid & 3, fr = lane & 15, fq = lane >> 4;
;     const int K = g.K, nt = K / BK;
;     unsigned voffA[2], voffB[2];
; #pragma unroll
;     for (int i = 0; i < 2; ++i) { int R, C; stage_rc(tid * 16 + i * 8192, R, C); const int Rb = Epi::PERM ? ((R & ~31) + perm32(R & 31)) : R; voffA[i] = (unsigned)(R * K + C) * 2u; voffB[i] = (unsigned)(Rb * K + C) * 2u; }
;     const size_t kstep = (size_t)(BK * 2);
;     const size_t hstep = (size_t)HALF * K * 2;
;     const size_t tstep = 2 * hstep;
;     const unsigned ldsw = (unsigned)wid * 1024u;
;     const int aoff = lds_byte(wr * 64 + fr, fq * 8), boff = lds_byte(wc * 32 + fr, fq * 8);
.LBB0_158:
	s_or_b64 exec, exec, s[4:5]
	s_lshr_b32 s97, s54, 6
	s_cmpk_lt_i32 s2, 0x50c
	v_mov_b32_e32 v8, v254
	s_cselect_b64 s[4:5], -1, 0
	s_waitcnt lgkmcnt(0)
	s_barrier
	s_cselect_b32 s100, 1, 0
	s_cmpk_gt_u32 s2, 0xbf
	s_cbranch_scc1 .Ltaild1_0_skip
	v_writelane_b32 v255, s4, 17
	v_writelane_b32 v255, s5, 18
	v_writelane_b32 v255, s6, 19
	v_writelane_b32 v255, s7, 20
	v_writelane_b32 v255, s8, 21
	v_writelane_b32 v255, s9, 22
	v_writelane_b32 v255, s10, 23
	v_writelane_b32 v255, s11, 24
	v_writelane_b32 v255, s12, 25
	v_writelane_b32 v255, s13, 26
	v_writelane_b32 v255, s14, 27
	v_writelane_b32 v255, s15, 28
	v_writelane_b32 v255, s16, 29
	v_writelane_b32 v255, s17, 30
	v_writelane_b32 v255, s18, 31
	v_writelane_b32 v255, s19, 32
	v_writelane_b32 v255, s20, 33
	v_writelane_b32 v255, s21, 34
	v_writelane_b32 v255, s22, 35
	v_writelane_b32 v255, s23, 36
	v_writelane_b32 v255, s24, 37
	v_writelane_b32 v255, s25, 38
	v_writelane_b32 v255, s26, 39
	v_writelane_b32 v255, s27, 40
	v_writelane_b32 v255, s28, 41
	v_writelane_b32 v255, s29, 42
	v_writelane_b32 v255, s30, 43
	v_writelane_b32 v255, s31, 44
	v_writelane_b32 v255, s36, 45
	v_writelane_b32 v255, s37, 46
	v_writelane_b32 v255, s38, 47
	v_writelane_b32 v255, s39, 48
	v_writelane_b32 v255, s40, 49
	v_writelane_b32 v255, s41, 50
	v_writelane_b32 v255, s42, 51
	v_writelane_b32 v255, s43, 52
	v_writelane_b32 v255, s44, 53
	v_writelane_b32 v255, s45, 54
	v_writelane_b32 v255, s46, 55
	v_writelane_b32 v255, s47, 56
	v_writelane_b32 v255, s48, 57
	v_writelane_b32 v255, s49, 58
	v_writelane_b32 v255, s50, 59
	v_writelane_b32 v255, s51, 60
	s_mov_b32 s98, m0
	s_and_b32 s4, s2, 7
	s_lshr_b32 s5, s2, 3
	s_and_b32 s6, s5, 3
	s_lshr_b32 s5, s5, 2
	s_lshl_b32 s5, s5, 3
	s_add_u32 s5, s5, s4
	s_and_b32 s7, s5, 3
	s_lshr_b32 s8, s5, 2
	s_mov_b32 s9, 0x28
	s_cmp_eq_u32 s8, 1
	s_cselect_b32 s9, 0x52, s9
	s_cmp_eq_u32 s8, 2
	s_cselect_b32 s9, 0x7c, s9
	s_cmp_eq_u32 s8, 3
	s_cselect_b32 s9, 0xa6, s9
	s_cmp_eq_u32 s8, 4
	s_cselect_b32 s9, 0x2c8, s9
	s_cmp_eq_u32 s8, 5
	s_cselect_b32 s9, 0x2f1, s9
	s_cmp_eq_u32 s8, 6
	s_cselect_b32 s9, 0x31a, s9
	s_cmp_eq_u32 s8, 7
	s_cselect_b32 s9, 0x742, s9
	s_cmp_eq_u32 s8, 8
	s_cselect_b32 s9, 0x29, s9
	s_cmp_eq_u32 s8, 9
	s_cselect_b32 s9, 0x53, s9
	s_cmp_eq_u32 s8, 10
	s_cselect_b32 s9, 0x7d, s9
	s_cmp_eq_u32 s8, 11
	s_cselect_b32 s9, 0xa7, s9
	s_and_b32 s10, s9, 0x1ff
	s_lshr_b32 s11, s9, 9
	s_lshl_b32 s12, s10, 8
	s_lshl_b32 s4, s7, 6
	s_add_u32 s12, s12, s4
	s_lshl_b32 s13, s11, 8
	s_lshl_b32 s4, s6, 6
	s_add_u32 s13, s13, s4
	s_mul_i32 s4, s12, 0x1600
	s_add_u32 s4, s4, 0x19548000
	s_add_u32 s16, s34, s4
	s_addc_u32 s17, s35, 0
	s_mul_i32 s4, s13, 0x1600
	s_add_u32 s4, s4, 0x14e00000
	s_add_u32 s18, s34, s4
	s_addc_u32 s19, s35, 0
	s_lshl_b32 s4, s12, 12
	s_lshl_b32 s5, s13, 2
	s_add_u32 s4, s4, s5
	s_add_u32 s20, s34, s4
	s_addc_u32 s21, s35, 0
	s_lshr_b32 s15, s33, 6
	s_and_b32 s27, s15, 1
	s_bfe_u32 s29, s15, 0x10001
	s_lshr_b32 s31, s15, 2
	v_and_b32_e32 v0, 31, v254
	v_lshrrev_b32_e32 v1, 5, v254
	v_mul_u32_u24_e32 v2, 0x90, v0
	v_lshl_add_u32 v2, v1, 4, v2
	s_mul_i32 s4, s27, 0x1200
	s_lshl_b32 s5, s31, 6
	s_add_u32 s4, s4, s5
	s_mul_i32 s6, s29, 0x1200
	s_add_u32 s6, s6, s5
	s_add_u32 s6, s6, 0x2400
	v_add_u32_e32 v3, s6, v2
	v_add_u32_e32 v2, s4, v2
	s_lshl_b32 s4, s27, 17
	s_lshl_b32 s5, s31, 16
	s_add_u32 s4, s4, s5
	s_lshl_b32 s5, s29, 7
	s_add_u32 s4, s4, s5
	v_lshlrev_b32_e32 v4, 14, v1
	v_lshl_add_u32 v4, v0, 2, v4
	v_add_u32_e32 v4, s4, v4
	v_mov_b32_e32 v72, v4
	v_add_u32_e32 v73, 0x1000, v4
	v_add_u32_e32 v74, 0x2000, v4
	v_add_u32_e32 v75, 0x3000, v4
	v_add_u32_e32 v76, 0x8000, v4
	v_add_u32_e32 v77, 0x9000, v4
	v_add_u32_e32 v78, 0xa000, v4
	v_add_u32_e32 v79, 0xb000, v4
	global_load_dword v64, v72, s[20:21]
	global_load_dword v65, v73, s[20:21]
	global_load_dword v66, v74, s[20:21]
	global_load_dword v67, v75, s[20:21]
	global_load_dword v68, v76, s[20:21]
	global_load_dword v69, v77, s[20:21]
	global_load_dword v70, v78, s[20:21]
	global_load_dword v71, v79, s[20:21]
	s_movk_i32 s48, 0x71c8
	s_mov_b32 s7, 0x1600
	s_movk_i32 s36, 0x80
	s_mov_b32 s37, 0
	s_lshl_b32 s4, s15, 6
	s_mov_b64 s[42:43], s[16:17]
	s_lshl_b32 s24, s15, 10
	v_add_u32_e32 v5, s4, v254
	v_mul_lo_u32 v6, v5, s48
	v_lshrrev_b32_e32 v6, 18, v6
	v_mul_u32_u24_e32 v7, 9, v6
	v_sub_u32_e32 v5, v5, v7
	v_cmp_ne_u32_e64 s[22:23], 8, v5
	s_nop 1
	v_cndmask_b32_e64 v5, 0, v5, s[22:23]
	v_mul_lo_u32 v6, v6, s7
	v_lshl_add_u32 v10, v5, 4, v6
	v_mov_b32_e32 v11, 0
	v_lshl_add_u64 v[10:11], s[42:43], 0, v[10:11]
	s_lshl_b32 s4, s15, 6
	s_lshl_b32 s25, s15, 10
	s_movk_i32 s5, 0xffc0
	s_cmp_eq_u32 s15, 0
	s_cselect_b32 s5, 0x200, s5
	s_cselect_b32 s42, s16, s18
	s_cselect_b32 s43, s17, s19
	s_add_u32 s4, s4, s5
	s_add_u32 s25, s25, 0x2000
	v_add_u32_e32 v5, s4, v254
	v_mul_lo_u32 v6, v5, s48
	v_lshrrev_b32_e32 v6, 18, v6
	v_mul_u32_u24_e32 v7, 9, v6
	v_sub_u32_e32 v5, v5, v7
	v_cmp_ne_u32_e64 s[22:23], 8, v5
	s_nop 1
	v_cndmask_b32_e64 v5, 0, v5, s[22:23]
	v_mul_lo_u32 v6, v6, s7
	v_lshl_add_u32 v12, v5, 4, v6
	v_mov_b32_e32 v13, 0
	v_lshl_add_u64 v[12:13], s[42:43], 0, v[12:13]
	s_lshl_b32 s4, s15, 4
	s_add_u32 s4, s4, 0x1c0
	s_mov_b64 s[42:43], s[18:19]
	s_lshl_b32 s26, s15, 8
	s_add_u32 s26, s26, 0x4000
	v_add_u32_e32 v5, s4, v254
	v_mul_lo_u32 v6, v5, s48
	v_lshrrev_b32_e32 v6, 18, v6
	v_mul_u32_u24_e32 v7, 9, v6
	v_sub_u32_e32 v5, v5, v7
	v_cmp_ne_u32_e64 s[22:23], 8, v5
	s_nop 1
	v_cndmask_b32_e64 v5, 0, v5, s[22:23]
	v_mul_lo_u32 v6, v6, s7
	v_lshl_add_u32 v14, v5, 4, v6
	v_mov_b32_e32 v15, 0
	v_lshl_add_u64 v[14:15], s[42:43], 0, v[14:15]
	s_mov_b32 s28, 0x0
	s_add_u32 m0, s28, s24
; template <class Epi>
; DI void gemm_phase(int wv, LAS unsigned char* lds, const Gemm g, const StaticOrder& S, const Epi& E) {
;     ...
;     for (;;) {
;         const bool has_next = S.next(ui + 1, nxt);
;         const char* nA = has_next ? (const char*)g.A + (size_t)nxt.pm * tstep : cA; const char* nB = has_next ? (const char*)g.Bt + (size_t)nxt.pn * tstep : cB;
;         for (int t = 0; t < nt; t += 2) {
;             const bool last = (t == nt - 2);
;             const char* a1 = cA + (size_t)(t + 1) * kstep;
;             const char* a2 = last ? nA : cA + (size_t)(t + 2) * kstep; const char* b2 = last ? nB : cB + (size_t)(t + 2) * kstep;
;             const char* a3 = a2 + kstep; const char* b3 = b2 + kstep;
;             PG8_LDB(B0, 0, 0); PG8_SCHED; PG8_LDA(At, 0, 0); PG8_STAGE(PG8_SA(1, 1), a1 + hstep, voffA);
;             PG8_WAIT_L(8); PG8_BAR; PG8_WAIT_L(0); PG8_MMA(0, 0, At, B0); PG8_BAR; PG8_SCHED;
;             PG8_LDB(B1, 0, 1); PG8_STAGE(PG8_SB(0, 0), b2, voffB);
;             PG8_BAR; PG8_WAIT_L(0); PG8_MMA(0, 1, At, B1); PG8_BAR;
;             PG8_LDA(At, 0, 1); PG8_STAGE(PG8_SA(0, 0), a2, voffA);
;             PG8_BAR; PG8_WAIT_L(0); PG8_MMA(1, 0, At, B0); PG8_BAR; PG8_SCHED;
;             PG8_STAGE(PG8_SB(0, 1), b2 + hstep, voffB);
;             PG8_WAIT_V(6); PG8_BAR; PG8_MMA(1, 1, At, B1); PG8_BAR;
;             PG8_LDB(B0, 1, 0); PG8_SCHED; PG8_LDA(At, 1, 0); PG8_STAGE(PG8_SA(0, 1), a2 + hstep, voffA);
;             PG8_WAIT_L(8); PG8_BAR; PG8_WAIT_L(0); PG8_MMA(0, 0, At, B0); PG8_BAR; PG8_SCHED;
;             PG8_LDB(B1, 1, 1); PG8_STAGE(PG8_SB(1, 0), b3, voffB);
;             PG8_BAR; PG8_WAIT_L(0); PG8_MMA(0, 1, At, B1); PG8_BAR;
;             PG8_LDA(At, 1, 1); PG8_STAGE(PG8_SA(1, 0), a3, voffA);
;             PG8_BAR; PG8_WAIT_L(0); PG8_MMA(1, 0, At, B0); PG8_BAR; PG8_SCHED;
;             PG8_STAGE(PG8_SB(1, 1), b3 + hstep, voffB);
;             PG8_WAIT_V(6); PG8_BAR; PG8_MMA(1, 1, At, B1); PG8_BAR;
;     DI void operator()(const AccT& acc, const Unit& u, int wr, int wc, int fr, int fq) const {
; #pragma unroll
;         for (int ai = 0; ai < 2; ++ai) {
;             f32x4 h[4][2][2];
;             float* base = H + ((size_t)u.pm * 256 + ai * 128 + wr * 64 + fr) * 1024 + u.pn * 256 + wc * 32 + 4 * fq;
; #pragma unroll
;             for (int m = 0; m < 4; ++m)
; #pragma unroll
;                 for (int bj = 0; bj < 2; ++bj)
	s_nop 0
	global_load_lds_dwordx4 v[10:11], off
	v_lshl_add_u64 v[10:11], v[10:11], 0, s[36:37]
	s_add_u32 m0, s28, s25
	s_nop 0
	global_load_lds_dwordx4 v[12:13], off
	v_lshl_add_u64 v[12:13], v[12:13], 0, s[36:37]
	s_add_u32 m0, s28, s26
	s_mov_b64 exec, 0xffff
	global_load_lds_dwordx4 v[14:15], off
	s_mov_b64 exec, -1
	v_lshl_add_u64 v[14:15], v[14:15], 0, s[36:37]
	s_mov_b32 s28, 0x4800
	s_add_u32 m0, s28, s24
	s_nop 0
	global_load_lds_dwordx4 v[10:11], off
	v_lshl_add_u64 v[10:11], v[10:11], 0, s[36:37]
	s_add_u32 m0, s28, s25
	s_nop 0
	global_load_lds_dwordx4 v[12:13], off
	v_lshl_add_u64 v[12:13], v[12:13], 0, s[36:37]
	s_add_u32 m0, s28, s26
	s_mov_b64 exec, 0xffff
	global_load_lds_dwordx4 v[14:15], off
	s_mov_b64 exec, -1
	v_lshl_add_u64 v[14:15], v[14:15], 0, s[36:37]
	s_mov_b32 s28, 0x9000
	s_add_u32 m0, s28, s24
	s_nop 0
	global_load_lds_dwordx4 v[10:11], off
	v_lshl_add_u64 v[10:11], v[10:11], 0, s[36:37]
	s_add_u32 m0, s28, s25
	s_nop 0
	global_load_lds_dwordx4 v[12:13], off
	v_lshl_add_u64 v[12:13], v[12:13], 0, s[36:37]
	s_add_u32 m0, s28, s26
	s_mov_b64 exec, 0xffff
	global_load_lds_dwordx4 v[14:15], off
	s_mov_b64 exec, -1
	v_lshl_add_u64 v[14:15], v[14:15], 0, s[36:37]
	s_mov_b32 s28, 0xd800
	s_add_u32 m0, s28, s24
	s_nop 0
	global_load_lds_dwordx4 v[10:11], off
	v_lshl_add_u64 v[10:11], v[10:11], 0, s[36:37]
	s_add_u32 m0, s28, s25
	s_nop 0
	global_load_lds_dwordx4 v[12:13], off
	v_lshl_add_u64 v[12:13], v[12:13], 0, s[36:37]
	s_add_u32 m0, s28, s26
	s_mov_b64 exec, 0xffff
	global_load_lds_dwordx4 v[14:15], off
	s_mov_b64 exec, -1
	v_lshl_add_u64 v[14:15], v[14:15], 0, s[36:37]
	s_mov_b32 s28, 0x12000
	s_add_u32 m0, s28, s24
	s_nop 0
	global_load_lds_dwordx4 v[10:11], off
	v_lshl_add_u64 v[10:11], v[10:11], 0, s[36:37]
	s_add_u32 m0, s28, s25
	s_nop 0
	global_load_lds_dwordx4 v[12:13], off
	v_lshl_add_u64 v[12:13], v[12:13], 0, s[36:37]
	s_add_u32 m0, s28, s26
	s_mov_b64 exec, 0xffff
	global_load_lds_dwordx4 v[14:15], off
	s_mov_b64 exec, -1
	v_lshl_add_u64 v[14:15], v[14:15], 0, s[36:37]
	v_mov_b32_e32 v32, 0
	v_mov_b32_e32 v33, 0
	v_mov_b32_e32 v34, 0
	v_mov_b32_e32 v35, 0
	v_mov_b32_e32 v36, 0
	v_mov_b32_e32 v37, 0
	v_mov_b32_e32 v38, 0
	v_mov_b32_e32 v39, 0
	v_mov_b32_e32 v40, 0
	v_mov_b32_e32 v41, 0
	v_mov_b32_e32 v42, 0
	v_mov_b32_e32 v43, 0
	v_mov_b32_e32 v44, 0
	v_mov_b32_e32 v45, 0
	v_mov_b32_e32 v46, 0
	v_mov_b32_e32 v47, 0
	s_mov_b32 s28, 0x16800
	s_mov_b32 s30, 0
	s_mov_b32 s14, 0
.Ltaild1_0_loop:
	s_waitcnt vmcnt(12)
	s_barrier
	s_add_u32 m0, s28, s24
	s_nop 0
	global_load_lds_dwordx4 v[10:11], off
	v_lshl_add_u64 v[10:11], v[10:11], 0, s[36:37]
	s_add_u32 m0, s28, s25
	s_nop 0
	global_load_lds_dwordx4 v[12:13], off
	v_lshl_add_u64 v[12:13], v[12:13], 0, s[36:37]
	s_add_u32 m0, s28, s26
	s_mov_b64 exec, 0xffff
	global_load_lds_dwordx4 v[14:15], off
	s_mov_b64 exec, -1
	v_lshl_add_u64 v[14:15], v[14:15], 0, s[36:37]
	v_add_u32_e32 v5, s30, v2
	v_add_u32_e32 v6, s30, v3
	ds_read_b128 v[48:51], v5
	ds_read_b128 v[56:59], v6
	ds_read_b128 v[52:55], v5 offset:32
	ds_read_b128 v[60:63], v6 offset:32
	s_waitcnt lgkmcnt(2)
	v_mfma_f32_32x32x16_bf16 v[32:47], v[48:51], v[56:59], v[32:47]
	s_waitcnt lgkmcnt(0)
	v_mfma_f32_32x32x16_bf16 v[32:47], v[52:55], v[60:63], v[32:47]
	s_add_u32 s28, s28, 0x4800
	s_cmp_eq_u32 s28, 0x1b000
	s_cselect_b32 s28, 0, s28
	s_add_u32 s30, s30, 0x4800
	s_cmp_eq_u32 s30, 0x1b000
	s_cselect_b32 s30, 0, s30
	s_add_u32 s14, s14, 1
	s_cmpk_lt_u32 s14, 0x27
	s_cbranch_scc1 .Ltaild1_0_loop
	s_waitcnt vmcnt(12)
	s_barrier
	v_add_u32_e32 v5, s30, v2
	v_add_u32_e32 v6, s30, v3
	ds_read_b128 v[48:51], v5
	ds_read_b128 v[56:59], v6
	ds_read_b128 v[52:55], v5 offset:32
	ds_read_b128 v[60:63], v6 offset:32
	s_waitcnt lgkmcnt(2)
	v_mfma_f32_32x32x16_bf16 v[32:47], v[48:51], v[56:59], v[32:47]
	s_waitcnt lgkmcnt(0)
	v_mfma_f32_32x32x16_bf16 v[32:47], v[52:55], v[60:63], v[32:47]
	s_add_u32 s30, s30, 0x4800
	s_cmp_eq_u32 s30, 0x1b000
	s_cselect_b32 s30, 0, s30
	s_waitcnt vmcnt(9)
	s_barrier
	v_add_u32_e32 v5, s30, v2
	v_add_u32_e32 v6, s30, v3
	ds_read_b128 v[48:51], v5
	ds_read_b128 v[56:59], v6
	ds_read_b128 v[52:55], v5 offset:32
	ds_read_b128 v[60:63], v6 offset:32
	s_waitcnt lgkmcnt(2)
	v_mfma_f32_32x32x16_bf16 v[32:47], v[48:51], v[56:59], v[32:47]
	s_waitcnt lgkmcnt(0)
	v_mfma_f32_32x32x16_bf16 v[32:47], v[52:55], v[60:63], v[32:47]
	s_add_u32 s30, s30, 0x4800
	s_cmp_eq_u32 s30, 0x1b000
	s_cselect_b32 s30, 0, s30
	s_waitcnt vmcnt(6)
	s_barrier
	v_add_u32_e32 v5, s30, v2
	v_add_u32_e32 v6, s30, v3
	ds_read_b128 v[48:51], v5
	ds_read_b128 v[56:59], v6
	ds_read_b128 v[52:55], v5 offset:32
	ds_read_b128 v[60:63], v6 offset:32
	s_waitcnt lgkmcnt(2)
	v_mfma_f32_32x32x16_bf16 v[32:47], v[48:51], v[56:59], v[32:47]
	s_waitcnt lgkmcnt(0)
	v_mfma_f32_32x32x16_bf16 v[32:47], v[52:55], v[60:63], v[32:47]
	s_add_u32 s30, s30, 0x4800
	s_cmp_eq_u32 s30, 0x1b000
	s_cselect_b32 s30, 0, s30
	s_waitcnt vmcnt(3)
	s_barrier
	v_add_u32_e32 v5, s30, v2
	v_add_u32_e32 v6, s30, v3
	ds_read_b128 v[48:51], v5
	ds_read_b128 v[56:59], v6
	ds_read_b128 v[52:55], v5 offset:32
	ds_read_b128 v[60:63], v6 offset:32
	s_waitcnt lgkmcnt(2)
	v_mfma_f32_32x32x16_bf16 v[32:47], v[48:51], v[56:59], v[32:47]
	s_waitcnt lgkmcnt(0)
	v_mfma_f32_32x32x16_bf16 v[32:47], v[52:55], v[60:63], v[32:47]
	s_add_u32 s30, s30, 0x4800
	s_cmp_eq_u32 s30, 0x1b000
	s_cselect_b32 s30, 0, s30
	s_waitcnt vmcnt(0)
	s_barrier
	v_add_u32_e32 v5, s30, v2
	v_add_u32_e32 v6, s30, v3
	ds_read_b128 v[48:51], v5
	ds_read_b128 v[56:59], v6
	ds_read_b128 v[52:55], v5 offset:32
	ds_read_b128 v[60:63], v6 offset:32
	s_waitcnt lgkmcnt(2)
	v_mfma_f32_32x32x16_bf16 v[32:47], v[48:51], v[56:59], v[32:47]
	s_waitcnt lgkmcnt(0)
	v_mfma_f32_32x32x16_bf16 v[32:47], v[52:55], v[60:63], v[32:47]
	s_add_u32 s30, s30, 0x4800
	s_cmp_eq_u32 s30, 0x1b000
	s_cselect_b32 s30, 0, s30
	s_and_b32 s4, s15, 3
	s_lshl_b32 s4, s4, 12
	s_add_u32 s4, s4, 0x1b000
	v_lshl_add_u32 v5, v254, 4, s4
	v_add_u32_e32 v6, 0x800, v5
	s_nop 15
	s_cmp_eq_u32 s31, 0
	s_cbranch_scc0 .Ltaild1_0_k1
	ds_write_b128 v5, v[40:43]
	ds_write_b128 v5, v[44:47] offset:1024
	s_waitcnt lgkmcnt(0)
	s_barrier
	ds_read_b128 v[48:51], v6
	ds_read_b128 v[52:55], v6 offset:1024
	s_waitcnt vmcnt(0) lgkmcnt(0)
	v_add_f32_e32 v32, v32, v48
	v_add_f32_e32 v33, v33, v49
	v_add_f32_e32 v34, v34, v50
	v_add_f32_e32 v35, v35, v51
	v_add_f32_e32 v36, v36, v52
	v_add_f32_e32 v37, v37, v53
	v_add_f32_e32 v38, v38, v54
	v_add_f32_e32 v39, v39, v55
	v_fmac_f32_e32 v64, 0.5, v32
	v_fmac_f32_e32 v65, 0.5, v33
	v_fmac_f32_e32 v66, 0.5, v34
	v_fmac_f32_e32 v67, 0.5, v35
	v_fmac_f32_e32 v68, 0.5, v36
	v_fmac_f32_e32 v69, 0.5, v37
	v_fmac_f32_e32 v70, 0.5, v38
	v_fmac_f32_e32 v71, 0.5, v39
	global_store_dword v72, v64, s[20:21]
	global_store_dword v73, v65, s[20:21]
	global_store_dword v74, v66, s[20:21]
	global_store_dword v75, v67, s[20:21]
	global_store_dword v76, v68, s[20:21]
	global_store_dword v77, v69, s[20:21]
	global_store_dword v78, v70, s[20:21]
	global_store_dword v79, v71, s[20:21]
	s_branch .Ltaild1_0_fin
;     DI bool next(int i, Unit& u) const {
;         const long L = (long)i * G + c; if (L >= nwg) return false;
;         int wgid = (int)L; { const int q = nwg / NXCD, r = nwg % NXCD, xcd = wgid % NXCD, off = wgid / NXCD; wgid = (xcd < r ? xcd * (q + 1) : r * (q + 1) + (xcd - r) * q) + off; }
;         const int nig = WGM * nN, gid = wgid / nig, fm = gid * WGM, gsz = (nM - fm) < WGM ? (nM - fm) : WGM;
;         u.pm = fm + ((wgid % nig) % gsz); u.pn = (wgid % nig) / gsz; return true;
;     }
;     DI void operator()(const AccT& acc, const Unit& u, int wr, int wc, int fr, int fq) const {
; #pragma unroll
;         for (int ai = 0; ai < 2; ++ai) {
;             f32x4 h[4][2][2];
;             float* base = H + ((size_t)u.pm * 256 + ai * 128 + wr * 64 + fr) * 1024 + u.pn * 256 + wc * 32 + 4 * fq;
; #pragma unroll
;             for (int m = 0; m < 4; ++m)
; #pragma unroll
;                 for (int bj = 0; bj < 2; ++bj)
; #pragma unroll
;                     for (int n = 0; n < 2; ++n) h[m][bj][n] = *(const f32x4*)(base + (size_t)m * 16 * 1024 + bj * 128 + n * 16);
;             __builtin_amdgcn_sched_barrier(0);
; #pragma unroll
;             for (int m = 0; m < 4; ++m)
; #pragma unroll
;                 for (int bj = 0; bj < 2; ++bj)
; #pragma unroll
;                     for (int n = 0; n < 2; ++n) *(f32x4*)(base + (size_t)m * 16 * 1024 + bj * 128 + n * 16) = h[m][bj][n] + acc[ai][bj][m][n] * alpha;
;         }
.Ltaild1_0_k1:
	ds_write_b128 v6, v[32:35]
	ds_write_b128 v6, v[36:39] offset:1024
	s_waitcnt lgkmcnt(0)
	s_barrier
	ds_read_b128 v[48:51], v5
	ds_read_b128 v[52:55], v5 offset:1024
	s_waitcnt vmcnt(0) lgkmcnt(0)
	v_add_f32_e32 v40, v40, v48
	v_add_f32_e32 v41, v41, v49
	v_add_f32_e32 v42, v42, v50
	v_add_f32_e32 v43, v43, v51
	v_add_f32_e32 v44, v44, v52
	v_add_f32_e32 v45, v45, v53
	v_add_f32_e32 v46, v46, v54
	v_add_f32_e32 v47, v47, v55
	v_fmac_f32_e32 v64, 0.5, v40
	v_fmac_f32_e32 v65, 0.5, v41
	v_fmac_f32_e32 v66, 0.5, v42
	v_fmac_f32_e32 v67, 0.5, v43
	v_fmac_f32_e32 v68, 0.5, v44
	v_fmac_f32_e32 v69, 0.5, v45
	v_fmac_f32_e32 v70, 0.5, v46
	v_fmac_f32_e32 v71, 0.5, v47
	global_store_dword v72, v64, s[20:21]
	global_store_dword v73, v65, s[20:21]
	global_store_dword v74, v66, s[20:21]
	global_store_dword v75, v67, s[20:21]
	global_store_dword v76, v68, s[20:21]
	global_store_dword v77, v69, s[20:21]
	global_store_dword v78, v70, s[20:21]
	global_store_dword v79, v71, s[20:21]
.Ltaild1_0_fin:
	s_barrier
	s_mov_b32 m0, s98
	v_readlane_b32 s4, v255, 17
	v_readlane_b32 s5, v255, 18
	v_readlane_b32 s6, v255, 19
	v_readlane_b32 s7, v255, 20
	v_readlane_b32 s8, v255, 21
	v_readlane_b32 s9, v255, 22
	v_readlane_b32 s10, v255, 23
	v_readlane_b32 s11, v255, 24
	v_readlane_b32 s12, v255, 25
	v_readlane_b32 s13, v255, 26
	v_readlane_b32 s14, v255, 27
	v_readlane_b32 s15, v255, 28
	v_readlane_b32 s16, v255, 29
	v_readlane_b32 s17, v255, 30
	v_readlane_b32 s18, v255, 31
	v_readlane_b32 s19, v255, 32
	v_readlane_b32 s20, v255, 33
	v_readlane_b32 s21, v255, 34
	v_readlane_b32 s22, v255, 35
	v_readlane_b32 s23, v255, 36
	v_readlane_b32 s24, v255, 37
	v_readlane_b32 s25, v255, 38
	v_readlane_b32 s26, v255, 39
	v_readlane_b32 s27, v255, 40
	v_readlane_b32 s28, v255, 41
	v_readlane_b32 s29, v255, 42
	v_readlane_b32 s30, v255, 43
	v_readlane_b32 s31, v255, 44
	v_readlane_b32 s36, v255, 45
	v_readlane_b32 s37, v255, 46
	v_readlane_b32 s38, v255, 47
	v_readlane_b32 s39, v255, 48
	v_readlane_b32 s40, v255, 49
	v_readlane_b32 s41, v255, 50
	v_readlane_b32 s42, v255, 51
	v_readlane_b32 s43, v255, 52
	v_readlane_b32 s44, v255, 53
	v_readlane_b32 s45, v255, 54
	v_readlane_b32 s46, v255, 55
	v_readlane_b32 s47, v255, 56
	v_readlane_b32 s48, v255, 57
	v_readlane_b32 s49, v255, 58
	v_readlane_b32 s50, v255, 59
	v_readlane_b32 s51, v255, 60
	v_mov_b32_e32 v8, v254
.Ltaild1_0_skip:
	s_cmp_lg_u32 s100, 0
	v_writelane_b32 v255, s4, 5
	v_add_u32_e32 v0, s33, v8
	s_cmpk_gt_i32 s2, 0x50b
	v_writelane_b32 v255, s5, 6
	v_readfirstlane_b32 s36, v0
	s_cbranch_scc1 .LBB0_182
	s_lshr_b32 s4, s3, 29
	s_add_i32 s6, s2, s4
	s_and_b32 s4, s6, -8
	s_sub_i32 s7, s2, s4
	s_cmp_gt_i32 s7, 3
	s_cbranch_scc0 .LBB0_161
	s_mul_i32 s4, s7, 0xa1
	s_add_i32 s8, s4, 4
	s_cbranch_execz .LBB0_162
	s_branch .LBB0_163

; #define PG8_STAGE(bufoff, gbase, voff) do { _Pragma("unroll") for (int _i = 0; _i < 2; ++_i) \
;         __builtin_amdgcn_global_load_lds((const unsigned*)((const char*)(gbase) + (voff)[_i]), (LAS unsigned*)(lds + (bufoff) + ldsw + _i * 8192), 16, 0, 0); } while (0)
; #define PG8_WAIT_V(n) asm volatile("s_waitcnt vmcnt(" #n ")" ::: "memory")
; #define PG8_BAR __builtin_amdgcn_s_barrier()
;     DI bool next(int i, Unit& u) const {
;         const long L = (long)i * G + c; if (L >= nwg) return false;
;         int wgid = (int)L; { const int q = nwg / NXCD, r = nwg % NXCD, xcd = wgid % NXCD, off = wgid / NXCD; wgid = (xcd < r ? xcd * (q + 1) : r * (q + 1) + (xcd - r) * q) + off; }
; template <class Epi>
; DI void gemm_phase(int wv, LAS unsigned char* lds, const Gemm g, const StaticOrder& S, const Epi& E) {
;     ...
;     const char* cA = (const char*)g.A + (size_t)cur.pm * tstep; const char* cB = (const char*)g.Bt + (size_t)cur.pn * tstep;
;     PG8_STAGE(PG8_SB(0, 0), cB, voffB); PG8_STAGE(PG8_SA(0, 0), cA, voffA); PG8_STAGE(PG8_SB(0, 1), cB + hstep, voffB); PG8_STAGE(PG8_SA(0, 1), cA + hstep, voffA);
;     if (wr == 1) PG8_BAR;
;     PG8_WAIT_V(4); PG8_BAR;
;     PG8_STAGE(PG8_SB(1, 0), cB + kstep, voffB); PG8_STAGE(PG8_SA(1, 0), cA + kstep, voffA); PG8_STAGE(PG8_SB(1, 1), cB + hstep + kstep, voffB);
;     PG8_WAIT_V(6); PG8_BAR;
.LBB0_165:
	s_lshl_b32 s8, s6, 6
	s_lshl_b32 s9, s6, 13
	s_lshl_b32 s6, s7, 5
	s_mov_b64 s[12:13], 0x80
	s_and_b32 s10, s6, 0x60
	s_add_i32 m0, s41, 0x18000
	v_lshl_add_u64 v[6:7], v[6:7], 0, s[12:13]
	s_lshl_b32 s14, s10, 7
	s_waitcnt vmcnt(4)
	s_barrier
	global_load_lds_dwordx4 v[6:7], off
	v_lshl_add_u64 v[4:5], v[4:5], 0, s[12:13]
	s_add_i32 m0, s41, 0x1a000
	s_add_i32 s50, s41, 0x8000
	s_add_i32 s51, s41, 0xa000
	global_load_lds_dwordx4 v[4:5], off
	v_lshl_add_u64 v[2:3], v[2:3], 0, s[12:13]
	s_mov_b32 m0, s50
	s_add_u32 s6, s20, 0xb0080
	global_load_lds_dwordx4 v[2:3], off
	v_lshl_add_u64 v[0:1], v[0:1], 0, s[12:13]
	s_mov_b32 m0, s51
	s_addc_u32 s7, s21, 0
	global_load_lds_dwordx4 v[0:1], off
	s_add_i32 m0, s41, 0x1c000
	v_lshl_add_u64 v[0:1], s[6:7], 0, v[128:129]
	global_load_lds_dwordx4 v[0:1], off
	v_lshl_add_u64 v[0:1], s[6:7], 0, v[130:131]
	s_add_i32 m0, s41, 0x1e000
	v_bfe_u32 v2, v8, 4, 2
	global_load_lds_dwordx4 v[0:1], off
	v_and_b32_e32 v0, 15, v8
	v_lshlrev_b32_e32 v1, 4, v2
	v_lshlrev_b32_e32 v3, 2, v8
	s_sext_i32_i8 s65, s4
	v_lshl_or_b32 v1, v0, 6, v1
	v_and_b32_e32 v3, 32, v3
	s_ashr_i32 s4, s8, 31
	v_bitop3_b32 v4, v1, s9, v3 bitop3:0xde
	v_bitop3_b32 v146, v1, s14, v3 bitop3:0xde
	v_or_b32_e32 v0, s8, v0
	v_mov_b32_e32 v1, s4
	v_lshlrev_b64 v[0:1], 12, v[0:1]
	v_lshl_add_u64 v[134:135], s[26:27], 0, v[0:1]
	v_lshrrev_b32_e32 v1, 1, v9
	v_mul_lo_u32 v0, v11, s5
	s_mov_b32 s4, 0xb000
	v_mad_u64_u32 v[0:1], s[8:9], v1, s4, v[0:1]
	v_or_b32_e32 v0, v0, v10
	v_add_lshl_u32 v132, v0, v12, 1
	v_lshrrev_b32_e32 v1, 1, v13
	v_mul_lo_u32 v0, v14, s5
	v_mad_u64_u32 v[0:1], s[4:5], v1, s4, v[0:1]
	s_mov_b64 s[6:7], 0xb0080
	s_waitcnt vmcnt(6)
	v_or_b32_e32 v0, v0, v15
	v_lshlrev_b32_e32 v2, 2, v2
	v_lshl_add_u64 v[136:137], v[132:133], 0, s[6:7]
	v_add_lshl_u32 v132, v0, v16, 1
	s_add_i32 s52, 0, 0x10000
	s_add_i32 s53, 0, 0x14000
	v_lshl_add_u64 v[138:139], v[132:133], 0, s[6:7]
	v_mov_b64_e32 v[140:141], 0x500
	v_mov_b64_e32 v[142:143], 0x4ff
	v_add_u32_e32 v147, s52, v146
	v_add_u32_e32 v148, 0, v4
	v_add_u32_e32 v149, s53, v146
	s_lshl_b32 s10, s10, 2
	v_lshlrev_b32_e32 v132, 2, v2
	s_mov_b32 s54, 0x20000
	s_mov_b32 s55, 0x30000
	s_mov_b64 s[14:15], 0x80000
	s_mov_b32 s58, 0x80000
	s_mov_b32 s59, 0x90000
	s_mov_b32 s60, 0xa0000
	s_mov_b32 s61, 0xb0000
	s_mov_b32 s62, s11
	s_barrier

; #define LAS __attribute__((address_space(3)))
;     DI bool next(int i, Unit& u) const {
;         const long L = (long)i * G + c; if (L >= nwg) return false;
;         int wgid = (int)L; { const int q = nwg / NXCD, r = nwg % NXCD, xcd = wgid % NXCD, off = wgid / NXCD; wgid = (xcd < r ? xcd * (q + 1) : r * (q + 1) + (xcd - r) * q) + off; }
;         const int nig = WGM * nN, gid = wgid / nig, fm = gid * WGM, gsz = (nM - fm) < WGM ? (nM - fm) : WGM;
;         u.pm = fm + ((wgid % nig) % gsz); u.pn = (wgid % nig) / gsz; return true;
;     }
; template <class Epi>
; DI void gemm_phase(int wv, LAS unsigned char* lds, const Gemm g, const StaticOrder& S, const Epi& E) {
;     const int tid = tid_(wv), wid = __builtin_amdgcn_readfirstlane(tid >> 6), lane = tid & 63, wr = wid >> 2, wc = wid & 3, fr = lane & 15, fq = lane >> 4;
;     const int K = g.K, nt = K / BK;
;     unsigned voffA[2], voffB[2];
; #pragma unroll
;     for (int i = 0; i < 2; ++i) { int R, C; stage_rc(tid * 16 + i * 8192, R, C); const int Rb = Epi::PERM ? ((R & ~31) + perm32(R & 31)) : R; voffA[i] = (unsigned)(R * K + C) * 2u; voffB[i] = (unsigned)(Rb * K + C) * 2u; }
;     const size_t kstep = (size_t)(BK * 2);
;     const size_t hstep = (size_t)HALF * K * 2;
;     const size_t tstep = 2 * hstep;
;     const unsigned ldsw = (unsigned)wid * 1024u;
;     const int aoff = lds_byte(wr * 64 + fr, fq * 8), boff = lds_byte(wc * 32 + fr, fq * 8);
.LBB0_1359:
	s_or_b64 exec, exec, s[6:7]
	v_readlane_b32 s8, v255, 5
	v_mov_b32_e32 v8, v254
	v_readlane_b32 s9, v255, 6
	s_waitcnt lgkmcnt(0)
	s_barrier
	s_cselect_b32 s100, 1, 0
	s_cmpk_gt_u32 s2, 0xbf
	s_cbranch_scc1 .Ltailout_0_skip
	v_writelane_b32 v255, s4, 17
	v_writelane_b32 v255, s5, 18
	v_writelane_b32 v255, s6, 19
	v_writelane_b32 v255, s7, 20
	v_writelane_b32 v255, s8, 21
	v_writelane_b32 v255, s9, 22
	v_writelane_b32 v255, s10, 23
	v_writelane_b32 v255, s11, 24
	v_writelane_b32 v255, s12, 25
	v_writelane_b32 v255, s13, 26
	v_writelane_b32 v255, s14, 27
	v_writelane_b32 v255, s15, 28
	v_writelane_b32 v255, s16, 29
	v_writelane_b32 v255, s17, 30
	v_writelane_b32 v255, s18, 31
	v_writelane_b32 v255, s19, 32
	v_writelane_b32 v255, s20, 33
	v_writelane_b32 v255, s21, 34
	v_writelane_b32 v255, s22, 35
	v_writelane_b32 v255, s23, 36
	v_writelane_b32 v255, s24, 37
	v_writelane_b32 v255, s25, 38
	v_writelane_b32 v255, s26, 39
	v_writelane_b32 v255, s27, 40
	v_writelane_b32 v255, s28, 41
	v_writelane_b32 v255, s29, 42
	v_writelane_b32 v255, s30, 43
	v_writelane_b32 v255, s31, 44
	v_writelane_b32 v255, s36, 45
	v_writelane_b32 v255, s37, 46
	v_writelane_b32 v255, s38, 47
	v_writelane_b32 v255, s39, 48
	v_writelane_b32 v255, s40, 49
	v_writelane_b32 v255, s41, 50
	v_writelane_b32 v255, s42, 51
	v_writelane_b32 v255, s43, 52
	v_writelane_b32 v255, s44, 53
	v_writelane_b32 v255, s45, 54
	v_writelane_b32 v255, s46, 55
	v_writelane_b32 v255, s47, 56
	v_writelane_b32 v255, s48, 57
	v_writelane_b32 v255, s49, 58
	v_writelane_b32 v255, s50, 59
	v_writelane_b32 v255, s51, 60
	s_mov_b32 s98, m0
	s_and_b32 s4, s2, 7
	s_lshr_b32 s5, s2, 3
	s_and_b32 s6, s5, 3
	s_lshr_b32 s5, s5, 2
	s_lshl_b32 s5, s5, 3
	s_add_u32 s5, s5, s4
	s_and_b32 s7, s5, 3
	s_lshr_b32 s8, s5, 2
	s_mov_b32 s9, 0x28
	s_cmp_eq_u32 s8, 1
	s_cselect_b32 s9, 0x52, s9
	s_cmp_eq_u32 s8, 2
	s_cselect_b32 s9, 0x7c, s9
	s_cmp_eq_u32 s8, 3
	s_cselect_b32 s9, 0xa6, s9
	s_cmp_eq_u32 s8, 4
	s_cselect_b32 s9, 0x2c8, s9
	s_cmp_eq_u32 s8, 5
	s_cselect_b32 s9, 0x2f1, s9
	s_cmp_eq_u32 s8, 6
	s_cselect_b32 s9, 0x31a, s9
	s_cmp_eq_u32 s8, 7
	s_cselect_b32 s9, 0x742, s9
	s_cmp_eq_u32 s8, 8
	s_cselect_b32 s9, 0x29, s9
	s_cmp_eq_u32 s8, 9
	s_cselect_b32 s9, 0x53, s9
	s_cmp_eq_u32 s8, 10
	s_cselect_b32 s9, 0x7d, s9
	s_cmp_eq_u32 s8, 11
	s_cselect_b32 s9, 0xa7, s9
	s_and_b32 s10, s9, 0x1ff
	s_lshr_b32 s11, s9, 9
	s_lshl_b32 s12, s10, 8
	s_lshl_b32 s4, s7, 6
	s_add_u32 s12, s12, s4
	s_lshl_b32 s13, s11, 8
	s_lshl_b32 s4, s6, 6
	s_add_u32 s13, s13, s4
	s_mul_i32 s4, s12, 0x800
	s_add_u32 s4, s4, 0x19548000
	s_add_u32 s16, s34, s4
	s_addc_u32 s17, s35, 0
	s_mul_i32 s4, s13, 0x800
	s_add_u32 s4, s4, 0x16a20000
	s_add_u32 s18, s34, s4
	s_addc_u32 s19, s35, 0
	s_lshl_b32 s4, s12, 12
	s_lshl_b32 s5, s13, 2
	s_add_u32 s4, s4, s5
	s_add_u32 s20, s34, s4
	s_addc_u32 s21, s35, 0
	s_lshr_b32 s15, s33, 6
	s_and_b32 s27, s15, 1
	s_bfe_u32 s29, s15, 0x10001
	s_lshr_b32 s31, s15, 2
	v_and_b32_e32 v0, 31, v254
	v_lshrrev_b32_e32 v1, 5, v254
	v_mul_u32_u24_e32 v2, 0x90, v0
	v_lshl_add_u32 v2, v1, 4, v2
	s_mul_i32 s4, s27, 0x1200
	s_lshl_b32 s5, s31, 6
	s_add_u32 s4, s4, s5
	s_mul_i32 s6, s29, 0x1200
	s_add_u32 s6, s6, s5
	s_add_u32 s6, s6, 0x2400
	v_add_u32_e32 v3, s6, v2
	v_add_u32_e32 v2, s4, v2
	s_lshl_b32 s4, s27, 17
	s_lshl_b32 s5, s31, 16
	s_add_u32 s4, s4, s5
	s_lshl_b32 s5, s29, 7
	s_add_u32 s4, s4, s5
	v_lshlrev_b32_e32 v4, 14, v1
	v_lshl_add_u32 v4, v0, 2, v4
	v_add_u32_e32 v4, s4, v4
	v_mov_b32_e32 v72, v4
	v_add_u32_e32 v73, 0x1000, v4
	v_add_u32_e32 v74, 0x2000, v4
	v_add_u32_e32 v75, 0x3000, v4
	v_add_u32_e32 v76, 0x8000, v4
	v_add_u32_e32 v77, 0x9000, v4
	v_add_u32_e32 v78, 0xa000, v4
	v_add_u32_e32 v79, 0xb000, v4
	global_load_dword v64, v72, s[20:21]
	global_load_dword v65, v73, s[20:21]
	global_load_dword v66, v74, s[20:21]
	global_load_dword v67, v75, s[20:21]
	global_load_dword v68, v76, s[20:21]
	global_load_dword v69, v77, s[20:21]
	global_load_dword v70, v78, s[20:21]
	global_load_dword v71, v79, s[20:21]
	s_movk_i32 s48, 0x71c8
	s_mov_b32 s7, 0x800
	s_movk_i32 s36, 0x80
	s_mov_b32 s37, 0
	s_lshl_b32 s4, s15, 6
	s_mov_b64 s[42:43], s[16:17]
	s_lshl_b32 s24, s15, 10
	v_add_u32_e32 v5, s4, v254
	v_mul_lo_u32 v6, v5, s48
	v_lshrrev_b32_e32 v6, 18, v6
	v_mul_u32_u24_e32 v7, 9, v6
	v_sub_u32_e32 v5, v5, v7
	v_cmp_ne_u32_e64 s[22:23], 8, v5
	s_nop 1
	v_cndmask_b32_e64 v5, 0, v5, s[22:23]
	v_mul_lo_u32 v6, v6, s7
	v_lshl_add_u32 v10, v5, 4, v6
	v_mov_b32_e32 v11, 0
	v_lshl_add_u64 v[10:11], s[42:43], 0, v[10:11]
	s_lshl_b32 s4, s15, 6
	s_lshl_b32 s25, s15, 10
	s_movk_i32 s5, 0xffc0
	s_cmp_eq_u32 s15, 0
	s_cselect_b32 s5, 0x200, s5
	s_cselect_b32 s42, s16, s18
	s_cselect_b32 s43, s17, s19
	s_add_u32 s4, s4, s5
	s_add_u32 s25, s25, 0x2000
	v_add_u32_e32 v5, s4, v254
	v_mul_lo_u32 v6, v5, s48
	v_lshrrev_b32_e32 v6, 18, v6
	v_mul_u32_u24_e32 v7, 9, v6
	v_sub_u32_e32 v5, v5, v7
	v_cmp_ne_u32_e64 s[22:23], 8, v5
	s_nop 1
	v_cndmask_b32_e64 v5, 0, v5, s[22:23]
	v_mul_lo_u32 v6, v6, s7
	v_lshl_add_u32 v12, v5, 4, v6
	v_mov_b32_e32 v13, 0
	v_lshl_add_u64 v[12:13], s[42:43], 0, v[12:13]
	s_lshl_b32 s4, s15, 4
	s_add_u32 s4, s4, 0x1c0
	s_mov_b64 s[42:43], s[18:19]
	s_lshl_b32 s26, s15, 8
	s_add_u32 s26, s26, 0x4000
	v_add_u32_e32 v5, s4, v254
	v_mul_lo_u32 v6, v5, s48
	v_lshrrev_b32_e32 v6, 18, v6
	v_mul_u32_u24_e32 v7, 9, v6
	v_sub_u32_e32 v5, v5, v7
	v_cmp_ne_u32_e64 s[22:23], 8, v5
	s_nop 1
	v_cndmask_b32_e64 v5, 0, v5, s[22:23]
	v_mul_lo_u32 v6, v6, s7
	v_lshl_add_u32 v14, v5, 4, v6
	v_mov_b32_e32 v15, 0
	v_lshl_add_u64 v[14:15], s[42:43], 0, v[14:15]
	s_mov_b32 s28, 0x0
	s_add_u32 m0, s28, s24
	s_nop 0
; #define PG8_STAGE(bufoff, gbase, voff) do { _Pragma("unroll") for (int _i = 0; _i < 2; ++_i) \
;         __builtin_amdgcn_global_load_lds((const unsigned*)((const char*)(gbase) + (voff)[_i]), (LAS unsigned*)(lds + (bufoff) + ldsw + _i * 8192), 16, 0, 0); } while (0)
; #define PG8_WAIT_V(n) asm volatile("s_waitcnt vmcnt(" #n ")" ::: "memory")
; #define PG8_BAR __builtin_amdgcn_s_barrier()
; template <class Epi>
; DI void gemm_phase(int wv, LAS unsigned char* lds, const Gemm g, const StaticOrder& S, const Epi& E) {
;     ...
;     PG8_STAGE(PG8_SB(0, 0), cB, voffB); PG8_STAGE(PG8_SA(0, 0), cA, voffA); PG8_STAGE(PG8_SB(0, 1), cB + hstep, voffB); PG8_STAGE(PG8_SA(0, 1), cA + hstep, voffA);
;     if (wr == 1) PG8_BAR;
;     PG8_WAIT_V(4); PG8_BAR;
;     PG8_STAGE(PG8_SB(1, 0), cB + kstep, voffB); PG8_STAGE(PG8_SA(1, 0), cA + kstep, voffA); PG8_STAGE(PG8_SB(1, 1), cB + hstep + kstep, voffB);
	global_load_lds_dwordx4 v[10:11], off
	v_lshl_add_u64 v[10:11], v[10:11], 0, s[36:37]
	s_add_u32 m0, s28, s25
	s_nop 0
	global_load_lds_dwordx4 v[12:13], off
	v_lshl_add_u64 v[12:13], v[12:13], 0, s[36:37]
	s_add_u32 m0, s28, s26
	s_mov_b64 exec, 0xffff
	global_load_lds_dwordx4 v[14:15], off
	s_mov_b64 exec, -1
	v_lshl_add_u64 v[14:15], v[14:15], 0, s[36:37]
	s_mov_b32 s28, 0x4800
	s_add_u32 m0, s28, s24
	s_nop 0
	global_load_lds_dwordx4 v[10:11], off
	v_lshl_add_u64 v[10:11], v[10:11], 0, s[36:37]
	s_add_u32 m0, s28, s25
	s_nop 0
	global_load_lds_dwordx4 v[12:13], off
	v_lshl_add_u64 v[12:13], v[12:13], 0, s[36:37]
	s_add_u32 m0, s28, s26
	s_mov_b64 exec, 0xffff
	global_load_lds_dwordx4 v[14:15], off
	s_mov_b64 exec, -1
	v_lshl_add_u64 v[14:15], v[14:15], 0, s[36:37]
	s_mov_b32 s28, 0x9000
	s_add_u32 m0, s28, s24
	s_nop 0
	global_load_lds_dwordx4 v[10:11], off
	v_lshl_add_u64 v[10:11], v[10:11], 0, s[36:37]
	s_add_u32 m0, s28, s25
	s_nop 0
	global_load_lds_dwordx4 v[12:13], off
	v_lshl_add_u64 v[12:13], v[12:13], 0, s[36:37]
	s_add_u32 m0, s28, s26
	s_mov_b64 exec, 0xffff
	global_load_lds_dwordx4 v[14:15], off
	s_mov_b64 exec, -1
	v_lshl_add_u64 v[14:15], v[14:15], 0, s[36:37]
	s_mov_b32 s28, 0xd800
	s_add_u32 m0, s28, s24
	s_nop 0
	global_load_lds_dwordx4 v[10:11], off
	v_lshl_add_u64 v[10:11], v[10:11], 0, s[36:37]
	s_add_u32 m0, s28, s25
	s_nop 0
	global_load_lds_dwordx4 v[12:13], off
	v_lshl_add_u64 v[12:13], v[12:13], 0, s[36:37]
	s_add_u32 m0, s28, s26
	s_mov_b64 exec, 0xffff
	global_load_lds_dwordx4 v[14:15], off
	s_mov_b64 exec, -1
	v_lshl_add_u64 v[14:15], v[14:15], 0, s[36:37]
	s_mov_b32 s28, 0x12000
	s_add_u32 m0, s28, s24
	s_nop 0
	global_load_lds_dwordx4 v[10:11], off
	v_lshl_add_u64 v[10:11], v[10:11], 0, s[36:37]
	s_add_u32 m0, s28, s25
	s_nop 0
	global_load_lds_dwordx4 v[12:13], off
	v_lshl_add_u64 v[12:13], v[12:13], 0, s[36:37]
	s_add_u32 m0, s28, s26
	s_mov_b64 exec, 0xffff
	global_load_lds_dwordx4 v[14:15], off
	s_mov_b64 exec, -1
	v_lshl_add_u64 v[14:15], v[14:15], 0, s[36:37]
	v_mov_b32_e32 v32, 0
	v_mov_b32_e32 v33, 0
	v_mov_b32_e32 v34, 0
	v_mov_b32_e32 v35, 0
	v_mov_b32_e32 v36, 0
	v_mov_b32_e32 v37, 0
	v_mov_b32_e32 v38, 0
	v_mov_b32_e32 v39, 0
	v_mov_b32_e32 v40, 0
	v_mov_b32_e32 v41, 0
	v_mov_b32_e32 v42, 0
	v_mov_b32_e32 v43, 0
	v_mov_b32_e32 v44, 0
	v_mov_b32_e32 v45, 0
	v_mov_b32_e32 v46, 0
	v_mov_b32_e32 v47, 0
	s_mov_b32 s28, 0x16800
	s_mov_b32 s30, 0
	s_mov_b32 s14, 0
; template <class Epi>
; DI void gemm_phase(int wv, LAS unsigned char* lds, const Gemm g, const StaticOrder& S, const Epi& E) {
;     ...
;     for (;;) {
;         const bool has_next = S.next(ui + 1, nxt);
;         const char* nA = has_next ? (const char*)g.A + (size_t)nxt.pm * tstep : cA; const char* nB = has_next ? (const char*)g.Bt + (size_t)nxt.pn * tstep : cB;
;         for (int t = 0; t < nt; t += 2) {
;             const bool last = (t == nt - 2);
;             const char* a1 = cA + (size_t)(t + 1) * kstep;
;             const char* a2 = last ? nA : cA + (size_t)(t + 2) * kstep; const char* b2 = last ? nB : cB + (size_t)(t + 2) * kstep;
;             const char* a3 = a2 + kstep; const char* b3 = b2 + kstep;
;             PG8_LDB(B0, 0, 0); PG8_SCHED; PG8_LDA(At, 0, 0); PG8_STAGE(PG8_SA(1, 1), a1 + hstep, voffA);
;             PG8_WAIT_L(8); PG8_BAR; PG8_WAIT_L(0); PG8_MMA(0, 0, At, B0); PG8_BAR; PG8_SCHED;
;             PG8_LDB(B1, 0, 1); PG8_STAGE(PG8_SB(0, 0), b2, voffB);
;             PG8_BAR; PG8_WAIT_L(0); PG8_MMA(0, 1, At, B1); PG8_BAR;
;             PG8_LDA(At, 0, 1); PG8_STAGE(PG8_SA(0, 0), a2, voffA);
;             PG8_BAR; PG8_WAIT_L(0); PG8_MMA(1, 0, At, B0); PG8_BAR; PG8_SCHED;
;             PG8_STAGE(PG8_SB(0, 1), b2 + hstep, voffB);
;             PG8_WAIT_V(6); PG8_BAR; PG8_MMA(1, 1, At, B1); PG8_BAR;
;             PG8_LDB(B0, 1, 0); PG8_SCHED; PG8_LDA(At, 1, 0); PG8_STAGE(PG8_SA(0, 1), a2 + hstep, voffA);
;             PG8_WAIT_L(8); PG8_BAR; PG8_WAIT_L(0); PG8_MMA(0, 0, At, B0); PG8_BAR; PG8_SCHED;
;             PG8_LDB(B1, 1, 1); PG8_STAGE(PG8_SB(1, 0), b3, voffB);
;             PG8_BAR; PG8_WAIT_L(0); PG8_MMA(0, 1, At, B1); PG8_BAR;
;             PG8_LDA(At, 1, 1); PG8_STAGE(PG8_SA(1, 0), a3, voffA);
;             PG8_BAR; PG8_WAIT_L(0); PG8_MMA(1, 0, At, B0); PG8_BAR; PG8_SCHED;
;             PG8_STAGE(PG8_SB(1, 1), b3 + hstep, voffB);
;             PG8_WAIT_V(6); PG8_BAR; PG8_MMA(1, 1, At, B1); PG8_BAR;
;     DI void operator()(const AccT& acc, const Unit& u, int wr, int wc, int fr, int fq) const {
; #pragma unroll
;         for (int ai = 0; ai < 2; ++ai) {
;             f32x4 h[4][2][2];
;             float* base = H + ((size_t)u.pm * 256 + ai * 128 + wr * 64 + fr) * 1024 + u.pn * 256 + wc * 32 + 4 * fq;
; #pragma unroll
;             for (int m = 0; m < 4; ++m)
; #pragma unroll
;                 for (int bj = 0; bj < 2; ++bj)
.Ltailout_0_loop:
	s_waitcnt vmcnt(12)
	s_barrier
	s_add_u32 m0, s28, s24
	s_nop 0
	global_load_lds_dwordx4 v[10:11], off
	v_lshl_add_u64 v[10:11], v[10:11], 0, s[36:37]
	s_add_u32 m0, s28, s25
	s_nop 0
	global_load_lds_dwordx4 v[12:13], off
	v_lshl_add_u64 v[12:13], v[12:13], 0, s[36:37]
	s_add_u32 m0, s28, s26
	s_mov_b64 exec, 0xffff
	global_load_lds_dwordx4 v[14:15], off
	s_mov_b64 exec, -1
	v_lshl_add_u64 v[14:15], v[14:15], 0, s[36:37]
	v_add_u32_e32 v5, s30, v2
	v_add_u32_e32 v6, s30, v3
	ds_read_b128 v[48:51], v5
	ds_read_b128 v[56:59], v6
	ds_read_b128 v[52:55], v5 offset:32
	ds_read_b128 v[60:63], v6 offset:32
	s_waitcnt lgkmcnt(2)
	v_mfma_f32_32x32x16_bf16 v[32:47], v[48:51], v[56:59], v[32:47]
	s_waitcnt lgkmcnt(0)
	v_mfma_f32_32x32x16_bf16 v[32:47], v[52:55], v[60:63], v[32:47]
	s_add_u32 s28, s28, 0x4800
	s_cmp_eq_u32 s28, 0x1b000
	s_cselect_b32 s28, 0, s28
	s_add_u32 s30, s30, 0x4800
	s_cmp_eq_u32 s30, 0x1b000
	s_cselect_b32 s30, 0, s30
	s_add_u32 s14, s14, 1
	s_cmpk_lt_u32 s14, 0xb
	s_cbranch_scc1 .Ltailout_0_loop
	s_waitcnt vmcnt(12)
	s_barrier
	v_add_u32_e32 v5, s30, v2
	v_add_u32_e32 v6, s30, v3
	ds_read_b128 v[48:51], v5
	ds_read_b128 v[56:59], v6
	ds_read_b128 v[52:55], v5 offset:32
	ds_read_b128 v[60:63], v6 offset:32
	s_waitcnt lgkmcnt(2)
	v_mfma_f32_32x32x16_bf16 v[32:47], v[48:51], v[56:59], v[32:47]
	s_waitcnt lgkmcnt(0)
	v_mfma_f32_32x32x16_bf16 v[32:47], v[52:55], v[60:63], v[32:47]
	s_add_u32 s30, s30, 0x4800
	s_cmp_eq_u32 s30, 0x1b000
	s_cselect_b32 s30, 0, s30
	s_waitcnt vmcnt(9)
	s_barrier
	v_add_u32_e32 v5, s30, v2
	v_add_u32_e32 v6, s30, v3
	ds_read_b128 v[48:51], v5
	ds_read_b128 v[56:59], v6
	ds_read_b128 v[52:55], v5 offset:32
	ds_read_b128 v[60:63], v6 offset:32
	s_waitcnt lgkmcnt(2)
	v_mfma_f32_32x32x16_bf16 v[32:47], v[48:51], v[56:59], v[32:47]
	s_waitcnt lgkmcnt(0)
	v_mfma_f32_32x32x16_bf16 v[32:47], v[52:55], v[60:63], v[32:47]
	s_add_u32 s30, s30, 0x4800
	s_cmp_eq_u32 s30, 0x1b000
	s_cselect_b32 s30, 0, s30
	s_waitcnt vmcnt(6)
	s_barrier
	v_add_u32_e32 v5, s30, v2
	v_add_u32_e32 v6, s30, v3
	ds_read_b128 v[48:51], v5
	ds_read_b128 v[56:59], v6
	ds_read_b128 v[52:55], v5 offset:32
	ds_read_b128 v[60:63], v6 offset:32
	s_waitcnt lgkmcnt(2)
	v_mfma_f32_32x32x16_bf16 v[32:47], v[48:51], v[56:59], v[32:47]
	s_waitcnt lgkmcnt(0)
	v_mfma_f32_32x32x16_bf16 v[32:47], v[52:55], v[60:63], v[32:47]
	s_add_u32 s30, s30, 0x4800
	s_cmp_eq_u32 s30, 0x1b000
	s_cselect_b32 s30, 0, s30
	s_waitcnt vmcnt(3)
	s_barrier
	v_add_u32_e32 v5, s30, v2
	v_add_u32_e32 v6, s30, v3
	ds_read_b128 v[48:51], v5
	ds_read_b128 v[56:59], v6
	ds_read_b128 v[52:55], v5 offset:32
	ds_read_b128 v[60:63], v6 offset:32
	s_waitcnt lgkmcnt(2)
	v_mfma_f32_32x32x16_bf16 v[32:47], v[48:51], v[56:59], v[32:47]
	s_waitcnt lgkmcnt(0)
	v_mfma_f32_32x32x16_bf16 v[32:47], v[52:55], v[60:63], v[32:47]
	s_add_u32 s30, s30, 0x4800
	s_cmp_eq_u32 s30, 0x1b000
	s_cselect_b32 s30, 0, s30
	s_waitcnt vmcnt(0)
	s_barrier
	v_add_u32_e32 v5, s30, v2
	v_add_u32_e32 v6, s30, v3
	ds_read_b128 v[48:51], v5
	ds_read_b128 v[56:59], v6
	ds_read_b128 v[52:55], v5 offset:32
	ds_read_b128 v[60:63], v6 offset:32
	s_waitcnt lgkmcnt(2)
	v_mfma_f32_32x32x16_bf16 v[32:47], v[48:51], v[56:59], v[32:47]
	s_waitcnt lgkmcnt(0)
	v_mfma_f32_32x32x16_bf16 v[32:47], v[52:55], v[60:63], v[32:47]
	s_add_u32 s30, s30, 0x4800
	s_cmp_eq_u32 s30, 0x1b000
	s_cselect_b32 s30, 0, s30
	s_and_b32 s4, s15, 3
	s_lshl_b32 s4, s4, 12
	s_add_u32 s4, s4, 0x1b000
	v_lshl_add_u32 v5, v254, 4, s4
	v_add_u32_e32 v6, 0x800, v5
	s_nop 15
	s_cmp_eq_u32 s31, 0
	s_cbranch_scc0 .Ltailout_0_k1
	ds_write_b128 v5, v[40:43]
	ds_write_b128 v5, v[44:47] offset:1024
	s_waitcnt lgkmcnt(0)
	s_barrier
	ds_read_b128 v[48:51], v6
	ds_read_b128 v[52:55], v6 offset:1024
	s_waitcnt vmcnt(0) lgkmcnt(0)
	v_add_f32_e32 v32, v32, v48
	v_add_f32_e32 v33, v33, v49
	v_add_f32_e32 v34, v34, v50
	v_add_f32_e32 v35, v35, v51
	v_add_f32_e32 v36, v36, v52
	v_add_f32_e32 v37, v37, v53
	v_add_f32_e32 v38, v38, v54
	v_add_f32_e32 v39, v39, v55
	v_fmac_f32_e32 v64, 1.0, v32
	v_fmac_f32_e32 v65, 1.0, v33
	v_fmac_f32_e32 v66, 1.0, v34
	v_fmac_f32_e32 v67, 1.0, v35
	v_fmac_f32_e32 v68, 1.0, v36
	v_fmac_f32_e32 v69, 1.0, v37
	v_fmac_f32_e32 v70, 1.0, v38
	v_fmac_f32_e32 v71, 1.0, v39
	global_store_dword v72, v64, s[20:21]
	global_store_dword v73, v65, s[20:21]
	global_store_dword v74, v66, s[20:21]
	global_store_dword v75, v67, s[20:21]
	global_store_dword v76, v68, s[20:21]
	global_store_dword v77, v69, s[20:21]
	global_store_dword v78, v70, s[20:21]
	global_store_dword v79, v71, s[20:21]
	s_branch .Ltailout_0_fin
.Ltailout_0_k1:
	ds_write_b128 v6, v[32:35]
	ds_write_b128 v6, v[36:39] offset:1024
	s_waitcnt lgkmcnt(0)
	s_barrier
	ds_read_b128 v[48:51], v5
	ds_read_b128 v[52:55], v5 offset:1024
	s_waitcnt vmcnt(0) lgkmcnt(0)
	v_add_f32_e32 v40, v40, v48
	v_add_f32_e32 v41, v41, v49
	v_add_f32_e32 v42, v42, v50
	v_add_f32_e32 v43, v43, v51
	v_add_f32_e32 v44, v44, v52
	v_add_f32_e32 v45, v45, v53
	v_add_f32_e32 v46, v46, v54
	v_add_f32_e32 v47, v47, v55
	v_fmac_f32_e32 v64, 1.0, v40
	v_fmac_f32_e32 v65, 1.0, v41
	v_fmac_f32_e32 v66, 1.0, v42
	v_fmac_f32_e32 v67, 1.0, v43
	v_fmac_f32_e32 v68, 1.0, v44
	v_fmac_f32_e32 v69, 1.0, v45
	v_fmac_f32_e32 v70, 1.0, v46
	v_fmac_f32_e32 v71, 1.0, v47
	global_store_dword v72, v64, s[20:21]
	global_store_dword v73, v65, s[20:21]
	global_store_dword v74, v66, s[20:21]
	global_store_dword v75, v67, s[20:21]
	global_store_dword v76, v68, s[20:21]
	global_store_dword v77, v69, s[20:21]
	global_store_dword v78, v70, s[20:21]
	global_store_dword v79, v71, s[20:21]

;     DI bool next(int i, Unit& u) const {
;         const long L = (long)i * G + c; if (L >= nwg) return false;
;         int wgid = (int)L; { const int q = nwg / NXCD, r = nwg % NXCD, xcd = wgid % NXCD, off = wgid / NXCD; wgid = (xcd < r ? xcd * (q + 1) : r * (q + 1) + (xcd - r) * q) + off; }
;         const int nig = WGM * nN, gid = wgid / nig, fm = gid * WGM, gsz = (nM - fm) < WGM ? (nM - fm) : WGM;
;         u.pm = fm + ((wgid % nig) % gsz); u.pn = (wgid % nig) / gsz; return true;
;     }
;     DI void operator()(const AccT& acc, const Unit& u, int wr, int wc, int fr, int fq) const {
; #pragma unroll
;         for (int ai = 0; ai < 2; ++ai) {
;             f32x4 h[4][2][2];
;             float* base = H + ((size_t)u.pm * 256 + ai * 128 + wr * 64 + fr) * 1024 + u.pn * 256 + wc * 32 + 4 * fq;
; #pragma unroll
;             for (int m = 0; m < 4; ++m)
; #pragma unroll
;                 for (int bj = 0; bj < 2; ++bj)
; #pragma unroll
;                     for (int n = 0; n < 2; ++n) h[m][bj][n] = *(const f32x4*)(base + (size_t)m * 16 * 1024 + bj * 128 + n * 16);
;             __builtin_amdgcn_sched_barrier(0);
; #pragma unroll
;             for (int m = 0; m < 4; ++m)
; #pragma unroll
;                 for (int bj = 0; bj < 2; ++bj)
; #pragma unroll
;                     for (int n = 0; n < 2; ++n) *(f32x4*)(base + (size_t)m * 16 * 1024 + bj * 128 + n * 16) = h[m][bj][n] + acc[ai][bj][m][n] * alpha;
;         }
.Ltailout_0_skip:
	s_cmp_lg_u32 s100, 0
	v_cndmask_b32_e64 v1, 0, 1, s[8:9]
	v_add_u32_e32 v0, s33, v8
	v_cmp_ne_u32_e64 s[6:7], 1, v1
	s_andn2_b64 vcc, exec, s[8:9]
	v_readfirstlane_b32 s8, v0
	s_cbranch_vccnz .LBB0_1379
	s_load_dwordx2 s[12:13], s[0:1], 0x128
	s_lshr_b32 s9, s3, 29
	s_add_i32 s9, s2, s9
	s_and_b32 s10, s9, -8
	s_sub_i32 s10, s2, s10
	s_cmp_gt_i32 s10, 3
	s_cbranch_scc0 .LBB0_1362
	s_mul_i32 s11, s10, 0xa1
	s_add_i32 s16, s11, 4
	s_cbranch_execz .LBB0_1363
	s_branch .LBB0_1364

; #define PG8_STAGE(bufoff, gbase, voff) do { _Pragma("unroll") for (int _i = 0; _i < 2; ++_i) \
;         __builtin_amdgcn_global_load_lds((const unsigned*)((const char*)(gbase) + (voff)[_i]), (LAS unsigned*)(lds + (bufoff) + ldsw + _i * 8192), 16, 0, 0); } while (0)
; #define PG8_WAIT_V(n) asm volatile("s_waitcnt vmcnt(" #n ")" ::: "memory")
; #define PG8_BAR __builtin_amdgcn_s_barrier()
;     DI bool next(int i, Unit& u) const {
;         const long L = (long)i * G + c; if (L >= nwg) return false;
;         int wgid = (int)L; { const int q = nwg / NXCD, r = nwg % NXCD, xcd = wgid % NXCD, off = wgid / NXCD; wgid = (xcd < r ? xcd * (q + 1) : r * (q + 1) + (xcd - r) * q) + off; }
; template <class Epi>
; DI void gemm_phase(int wv, LAS unsigned char* lds, const Gemm g, const StaticOrder& S, const Epi& E) {
;     ...
;     const char* cA = (const char*)g.A + (size_t)cur.pm * tstep; const char* cB = (const char*)g.Bt + (size_t)cur.pn * tstep;
;     PG8_STAGE(PG8_SB(0, 0), cB, voffB); PG8_STAGE(PG8_SA(0, 0), cA, voffA); PG8_STAGE(PG8_SB(0, 1), cB + hstep, voffB); PG8_STAGE(PG8_SA(0, 1), cA + hstep, voffA);
;     if (wr == 1) PG8_BAR;
;     PG8_WAIT_V(4); PG8_BAR;
;     PG8_STAGE(PG8_SB(1, 0), cB + kstep, voffB); PG8_STAGE(PG8_SA(1, 0), cA + kstep, voffA); PG8_STAGE(PG8_SB(1, 1), cB + hstep + kstep, voffB);
;     PG8_WAIT_V(6); PG8_BAR;
.LBB0_1366:
	s_lshl_b32 s14, s14, 5
	s_mov_b64 s[16:17], 0x80
	s_and_b32 s14, s14, 0x60
	s_add_i32 m0, s51, 0x18000
	v_lshl_add_u64 v[6:7], v[6:7], 0, s[16:17]
	s_lshl_b32 s20, s13, 6
	s_lshl_b32 s13, s13, 13
	s_lshl_b32 s21, s14, 7
	s_waitcnt vmcnt(4)
	s_barrier
	global_load_lds_dwordx4 v[6:7], off
	v_lshl_add_u64 v[4:5], v[4:5], 0, s[16:17]
	s_add_i32 m0, s51, 0x1a000
	s_add_i32 s55, s51, 0x8000
	s_add_i32 s58, s51, 0xa000
	global_load_lds_dwordx4 v[4:5], off
	v_lshl_add_u64 v[2:3], v[2:3], 0, s[16:17]
	s_mov_b32 m0, s55
	s_add_u32 s18, s64, 0x40080
	global_load_lds_dwordx4 v[2:3], off
	v_lshl_add_u64 v[0:1], v[0:1], 0, s[16:17]
	s_mov_b32 m0, s58
	s_addc_u32 s19, s65, 0
	global_load_lds_dwordx4 v[0:1], off
	s_add_i32 m0, s51, 0x1c000
	v_lshl_add_u64 v[0:1], s[18:19], 0, v[128:129]
	global_load_lds_dwordx4 v[0:1], off
	v_lshl_add_u64 v[0:1], s[18:19], 0, v[130:131]
	s_add_i32 m0, s51, 0x1e000
	v_bfe_u32 v2, v8, 4, 2
	global_load_lds_dwordx4 v[0:1], off
	v_and_b32_e32 v0, 15, v8
	v_lshlrev_b32_e32 v1, 4, v2
	v_lshlrev_b32_e32 v3, 2, v8
	v_lshl_or_b32 v1, v0, 6, v1
	v_and_b32_e32 v3, 32, v3
	s_ashr_i32 s18, s20, 31
	v_bitop3_b32 v4, v1, s13, v3 bitop3:0xde
	v_bitop3_b32 v146, v1, s21, v3 bitop3:0xde
	v_or_b32_e32 v0, s20, v0
	v_mov_b32_e32 v1, s18
	v_lshlrev_b64 v[0:1], 12, v[0:1]
	v_lshl_add_u64 v[134:135], s[26:27], 0, v[0:1]
	v_lshlrev_b32_e32 v0, 13, v9
	v_and_b32_e32 v0, 0x7fffc000, v0
	v_lshl_add_u32 v0, v10, 10, v0
	v_or_b32_e32 v0, v0, v11
	v_add_lshl_u32 v132, v0, v12, 1
	v_lshlrev_b32_e32 v0, 13, v13
	v_and_b32_e32 v0, 0x7fffc000, v0
	v_lshl_add_u32 v0, v14, 10, v0
	s_sext_i32_i8 s78, s12
	s_mov_b64 s[12:13], 0x40080
	s_waitcnt vmcnt(6)
	v_or_b32_e32 v0, v0, v15
	v_lshlrev_b32_e32 v2, 2, v2
	v_lshl_add_u64 v[136:137], v[132:133], 0, s[12:13]
	v_add_lshl_u32 v132, v0, v16, 1
	s_add_i32 s59, 0, 0x10000
	s_add_i32 s70, 0, 0x14000
	v_lshl_add_u64 v[138:139], v[132:133], 0, s[12:13]
	v_mov_b64_e32 v[140:141], 0x500
	v_mov_b64_e32 v[142:143], 0x4ff
	v_add_u32_e32 v147, s59, v146
	v_add_u32_e32 v148, 0, v4
	v_add_u32_e32 v149, s70, v146
	s_lshl_b32 s14, s14, 2
	v_lshlrev_b32_e32 v132, 2, v2
	s_mov_b32 s71, 0x20000
	s_mov_b32 s72, 0x30000
	s_mov_b64 s[18:19], 0x80000
	s_mov_b32 s73, 0x80000
	s_mov_b32 s74, 0x90000
	s_mov_b32 s75, 0xa0000
	s_mov_b32 s76, 0xb0000
	s_mov_b32 s77, s15
	s_barrier

; #define LAS __attribute__((address_space(3)))
;     DI bool next(int i, Unit& u) const {
;         const long L = (long)i * G + c; if (L >= nwg) return false;
;         int wgid = (int)L; { const int q = nwg / NXCD, r = nwg % NXCD, xcd = wgid % NXCD, off = wgid / NXCD; wgid = (xcd < r ? xcd * (q + 1) : r * (q + 1) + (xcd - r) * q) + off; }
;         const int nig = WGM * nN, gid = wgid / nig, fm = gid * WGM, gsz = (nM - fm) < WGM ? (nM - fm) : WGM;
;         u.pm = fm + ((wgid % nig) % gsz); u.pn = (wgid % nig) / gsz; return true;
;     }
; template <class Epi>
; DI void gemm_phase(int wv, LAS unsigned char* lds, const Gemm g, const StaticOrder& S, const Epi& E) {
;     const int tid = tid_(wv), wid = __builtin_amdgcn_readfirstlane(tid >> 6), lane = tid & 63, wr = wid >> 2, wc = wid & 3, fr = lane & 15, fq = lane >> 4;
;     const int K = g.K, nt = K / BK;
;     unsigned voffA[2], voffB[2];
; #pragma unroll
;     for (int i = 0; i < 2; ++i) { int R, C; stage_rc(tid * 16 + i * 8192, R, C); const int Rb = Epi::PERM ? ((R & ~31) + perm32(R & 31)) : R; voffA[i] = (unsigned)(R * K + C) * 2u; voffB[i] = (unsigned)(Rb * K + C) * 2u; }
;     const size_t kstep = (size_t)(BK * 2);
;     const size_t hstep = (size_t)HALF * K * 2;
;     const size_t tstep = 2 * hstep;
;     const unsigned ldsw = (unsigned)wid * 1024u;
;     const int aoff = lds_byte(wr * 64 + fr, fq * 8), boff = lds_byte(wc * 32 + fr, fq * 8);
.LBB0_1587:
	s_or_b64 exec, exec, s[16:17]
	v_mov_b32_e32 v8, v254
	s_waitcnt lgkmcnt(0)
	s_barrier
	s_cselect_b32 s100, 1, 0
	s_cmpk_gt_u32 s2, 0xbf
	s_cbranch_scc1 .Ltaild2_0_skip
	v_writelane_b32 v255, s4, 17
	v_writelane_b32 v255, s5, 18
	v_writelane_b32 v255, s6, 19
	v_writelane_b32 v255, s7, 20
	v_writelane_b32 v255, s8, 21
	v_writelane_b32 v255, s9, 22
	v_writelane_b32 v255, s10, 23
	v_writelane_b32 v255, s11, 24
	v_writelane_b32 v255, s12, 25
	v_writelane_b32 v255, s13, 26
	v_writelane_b32 v255, s14, 27
	v_writelane_b32 v255, s15, 28
	v_writelane_b32 v255, s16, 29
	v_writelane_b32 v255, s17, 30
	v_writelane_b32 v255, s18, 31
	v_writelane_b32 v255, s19, 32
	v_writelane_b32 v255, s20, 33
	v_writelane_b32 v255, s21, 34
	v_writelane_b32 v255, s22, 35
	v_writelane_b32 v255, s23, 36
	v_writelane_b32 v255, s24, 37
	v_writelane_b32 v255, s25, 38
	v_writelane_b32 v255, s26, 39
	v_writelane_b32 v255, s27, 40
	v_writelane_b32 v255, s28, 41
	v_writelane_b32 v255, s29, 42
	v_writelane_b32 v255, s30, 43
	v_writelane_b32 v255, s31, 44
	v_writelane_b32 v255, s36, 45
	v_writelane_b32 v255, s37, 46
	v_writelane_b32 v255, s38, 47
	v_writelane_b32 v255, s39, 48
	v_writelane_b32 v255, s40, 49
	v_writelane_b32 v255, s41, 50
	v_writelane_b32 v255, s42, 51
	v_writelane_b32 v255, s43, 52
	v_writelane_b32 v255, s44, 53
	v_writelane_b32 v255, s45, 54
	v_writelane_b32 v255, s46, 55
	v_writelane_b32 v255, s47, 56
	v_writelane_b32 v255, s48, 57
	v_writelane_b32 v255, s49, 58
	v_writelane_b32 v255, s50, 59
	v_writelane_b32 v255, s51, 60
	s_mov_b32 s98, m0
	s_and_b32 s4, s2, 7
	s_lshr_b32 s5, s2, 3
	s_and_b32 s6, s5, 3
	s_lshr_b32 s5, s5, 2
	s_lshl_b32 s5, s5, 3
	s_add_u32 s5, s5, s4
	s_and_b32 s7, s5, 3
	s_lshr_b32 s8, s5, 2
	s_mov_b32 s9, 0x28
	s_cmp_eq_u32 s8, 1
	s_cselect_b32 s9, 0x52, s9
	s_cmp_eq_u32 s8, 2
	s_cselect_b32 s9, 0x7c, s9
	s_cmp_eq_u32 s8, 3
	s_cselect_b32 s9, 0xa6, s9
	s_cmp_eq_u32 s8, 4
	s_cselect_b32 s9, 0x2c8, s9
	s_cmp_eq_u32 s8, 5
	s_cselect_b32 s9, 0x2f1, s9
	s_cmp_eq_u32 s8, 6
	s_cselect_b32 s9, 0x31a, s9
	s_cmp_eq_u32 s8, 7
	s_cselect_b32 s9, 0x742, s9
	s_cmp_eq_u32 s8, 8
	s_cselect_b32 s9, 0x29, s9
	s_cmp_eq_u32 s8, 9
	s_cselect_b32 s9, 0x53, s9
	s_cmp_eq_u32 s8, 10
	s_cselect_b32 s9, 0x7d, s9
	s_cmp_eq_u32 s8, 11
	s_cselect_b32 s9, 0xa7, s9
	s_and_b32 s10, s9, 0x1ff
	s_lshr_b32 s11, s9, 9
	s_lshl_b32 s12, s10, 8
	s_lshl_b32 s4, s7, 6
	s_add_u32 s12, s12, s4
	s_lshl_b32 s13, s11, 8
	s_lshl_b32 s4, s6, 6
	s_add_u32 s13, s13, s4
	s_mul_i32 s4, s12, 0x1600
	s_add_u32 s4, s4, 0x19548000
	s_add_u32 s16, s34, s4
	s_addc_u32 s17, s35, 0
	s_mul_i32 s4, s13, 0x1600
	s_add_u32 s4, s4, 0x15e80000
	s_add_u32 s18, s34, s4
	s_addc_u32 s19, s35, 0
	s_lshl_b32 s4, s12, 12
	s_lshl_b32 s5, s13, 2
	s_add_u32 s4, s4, s5
	s_add_u32 s20, s34, s4
	s_addc_u32 s21, s35, 0
	s_lshr_b32 s15, s33, 6
	s_and_b32 s27, s15, 1
	s_bfe_u32 s29, s15, 0x10001
	s_lshr_b32 s31, s15, 2
	v_and_b32_e32 v0, 31, v254
	v_lshrrev_b32_e32 v1, 5, v254
	v_mul_u32_u24_e32 v2, 0x90, v0
	v_lshl_add_u32 v2, v1, 4, v2
	s_mul_i32 s4, s27, 0x1200
	s_lshl_b32 s5, s31, 6
	s_add_u32 s4, s4, s5
	s_mul_i32 s6, s29, 0x1200
	s_add_u32 s6, s6, s5
	s_add_u32 s6, s6, 0x2400
	v_add_u32_e32 v3, s6, v2
	v_add_u32_e32 v2, s4, v2
	s_lshl_b32 s4, s27, 17
	s_lshl_b32 s5, s31, 16
	s_add_u32 s4, s4, s5
	s_lshl_b32 s5, s29, 7
	s_add_u32 s4, s4, s5
	v_lshlrev_b32_e32 v4, 14, v1
	v_lshl_add_u32 v4, v0, 2, v4
	v_add_u32_e32 v4, s4, v4
	v_mov_b32_e32 v72, v4
	v_add_u32_e32 v73, 0x1000, v4
	v_add_u32_e32 v74, 0x2000, v4
	v_add_u32_e32 v75, 0x3000, v4
	v_add_u32_e32 v76, 0x8000, v4
	v_add_u32_e32 v77, 0x9000, v4
	v_add_u32_e32 v78, 0xa000, v4
	v_add_u32_e32 v79, 0xb000, v4
	global_load_dword v64, v72, s[20:21]
	global_load_dword v65, v73, s[20:21]
	global_load_dword v66, v74, s[20:21]
	global_load_dword v67, v75, s[20:21]
	global_load_dword v68, v76, s[20:21]
	global_load_dword v69, v77, s[20:21]
	global_load_dword v70, v78, s[20:21]
	global_load_dword v71, v79, s[20:21]
	s_movk_i32 s48, 0x71c8
	s_mov_b32 s7, 0x1600
; #define PG8_STAGE(bufoff, gbase, voff) do { _Pragma("unroll") for (int _i = 0; _i < 2; ++_i) \
;         __builtin_amdgcn_global_load_lds((const unsigned*)((const char*)(gbase) + (voff)[_i]), (LAS unsigned*)(lds + (bufoff) + ldsw + _i * 8192), 16, 0, 0); } while (0)
; #define PG8_WAIT_V(n) asm volatile("s_waitcnt vmcnt(" #n ")" ::: "memory")
; #define PG8_BAR __builtin_amdgcn_s_barrier()
; template <class Epi>
; DI void gemm_phase(int wv, LAS unsigned char* lds, const Gemm g, const StaticOrder& S, const Epi& E) {
;     ...
;     for (int i = 0; i < 2; ++i) { int R, C; stage_rc(tid * 16 + i * 8192, R, C); const int Rb = Epi::PERM ? ((R & ~31) + perm32(R & 31)) : R; voffA[i] = (unsigned)(R * K + C) * 2u; voffB[i] = (unsigned)(Rb * K + C) * 2u; }
;     const size_t kstep = (size_t)(BK * 2);
;     const size_t hstep = (size_t)HALF * K * 2;
;     const size_t tstep = 2 * hstep;
;     const unsigned ldsw = (unsigned)wid * 1024u;
;     const int aoff = lds_byte(wr * 64 + fr, fq * 8), boff = lds_byte(wc * 32 + fr, fq * 8);
;     ...
;     PG8_STAGE(PG8_SB(0, 0), cB, voffB); PG8_STAGE(PG8_SA(0, 0), cA, voffA); PG8_STAGE(PG8_SB(0, 1), cB + hstep, voffB); PG8_STAGE(PG8_SA(0, 1), cA + hstep, voffA);
;     if (wr == 1) PG8_BAR;
;     PG8_WAIT_V(4); PG8_BAR;
;     PG8_STAGE(PG8_SB(1, 0), cB + kstep, voffB); PG8_STAGE(PG8_SA(1, 0), cA + kstep, voffA); PG8_STAGE(PG8_SB(1, 1), cB + hstep + kstep, voffB);
	s_movk_i32 s36, 0x80
	s_mov_b32 s37, 0
	s_lshl_b32 s4, s15, 6
	s_mov_b64 s[42:43], s[16:17]
	s_lshl_b32 s24, s15, 10
	v_add_u32_e32 v5, s4, v254
	v_mul_lo_u32 v6, v5, s48
	v_lshrrev_b32_e32 v6, 18, v6
	v_mul_u32_u24_e32 v7, 9, v6
	v_sub_u32_e32 v5, v5, v7
	v_cmp_ne_u32_e64 s[22:23], 8, v5
	s_nop 1
	v_cndmask_b32_e64 v5, 0, v5, s[22:23]
	v_mul_lo_u32 v6, v6, s7
	v_lshl_add_u32 v10, v5, 4, v6
	v_mov_b32_e32 v11, 0
	v_lshl_add_u64 v[10:11], s[42:43], 0, v[10:11]
	s_lshl_b32 s4, s15, 6
	s_lshl_b32 s25, s15, 10
	s_movk_i32 s5, 0xffc0
	s_cmp_eq_u32 s15, 0
	s_cselect_b32 s5, 0x200, s5
	s_cselect_b32 s42, s16, s18
	s_cselect_b32 s43, s17, s19
	s_add_u32 s4, s4, s5
	s_add_u32 s25, s25, 0x2000
	v_add_u32_e32 v5, s4, v254
	v_mul_lo_u32 v6, v5, s48
	v_lshrrev_b32_e32 v6, 18, v6
	v_mul_u32_u24_e32 v7, 9, v6
	v_sub_u32_e32 v5, v5, v7
	v_cmp_ne_u32_e64 s[22:23], 8, v5
	s_nop 1
	v_cndmask_b32_e64 v5, 0, v5, s[22:23]
	v_mul_lo_u32 v6, v6, s7
	v_lshl_add_u32 v12, v5, 4, v6
	v_mov_b32_e32 v13, 0
	v_lshl_add_u64 v[12:13], s[42:43], 0, v[12:13]
	s_lshl_b32 s4, s15, 4
	s_add_u32 s4, s4, 0x1c0
	s_mov_b64 s[42:43], s[18:19]
	s_lshl_b32 s26, s15, 8
	s_add_u32 s26, s26, 0x4000
	v_add_u32_e32 v5, s4, v254
	v_mul_lo_u32 v6, v5, s48
	v_lshrrev_b32_e32 v6, 18, v6
	v_mul_u32_u24_e32 v7, 9, v6
	v_sub_u32_e32 v5, v5, v7
	v_cmp_ne_u32_e64 s[22:23], 8, v5
	s_nop 1
	v_cndmask_b32_e64 v5, 0, v5, s[22:23]
	v_mul_lo_u32 v6, v6, s7
	v_lshl_add_u32 v14, v5, 4, v6
	v_mov_b32_e32 v15, 0
	v_lshl_add_u64 v[14:15], s[42:43], 0, v[14:15]
	s_mov_b32 s28, 0x0
	s_add_u32 m0, s28, s24
	s_nop 0
	global_load_lds_dwordx4 v[10:11], off
	v_lshl_add_u64 v[10:11], v[10:11], 0, s[36:37]
	s_add_u32 m0, s28, s25
	s_nop 0
	global_load_lds_dwordx4 v[12:13], off
	v_lshl_add_u64 v[12:13], v[12:13], 0, s[36:37]
	s_add_u32 m0, s28, s26
	s_mov_b64 exec, 0xffff
	global_load_lds_dwordx4 v[14:15], off
	s_mov_b64 exec, -1
	v_lshl_add_u64 v[14:15], v[14:15], 0, s[36:37]
	s_mov_b32 s28, 0x4800
	s_add_u32 m0, s28, s24
	s_nop 0
	global_load_lds_dwordx4 v[10:11], off
	v_lshl_add_u64 v[10:11], v[10:11], 0, s[36:37]
	s_add_u32 m0, s28, s25
	s_nop 0
	global_load_lds_dwordx4 v[12:13], off
	v_lshl_add_u64 v[12:13], v[12:13], 0, s[36:37]
	s_add_u32 m0, s28, s26
	s_mov_b64 exec, 0xffff
	global_load_lds_dwordx4 v[14:15], off
	s_mov_b64 exec, -1
	v_lshl_add_u64 v[14:15], v[14:15], 0, s[36:37]
	s_mov_b32 s28, 0x9000
	s_add_u32 m0, s28, s24
	s_nop 0
	global_load_lds_dwordx4 v[10:11], off
	v_lshl_add_u64 v[10:11], v[10:11], 0, s[36:37]
	s_add_u32 m0, s28, s25
	s_nop 0
	global_load_lds_dwordx4 v[12:13], off
	v_lshl_add_u64 v[12:13], v[12:13], 0, s[36:37]
	s_add_u32 m0, s28, s26
	s_mov_b64 exec, 0xffff
	global_load_lds_dwordx4 v[14:15], off
	s_mov_b64 exec, -1
	v_lshl_add_u64 v[14:15], v[14:15], 0, s[36:37]
	s_mov_b32 s28, 0xd800
	s_add_u32 m0, s28, s24
	s_nop 0
	global_load_lds_dwordx4 v[10:11], off
	v_lshl_add_u64 v[10:11], v[10:11], 0, s[36:37]
	s_add_u32 m0, s28, s25
	s_nop 0
	global_load_lds_dwordx4 v[12:13], off
	v_lshl_add_u64 v[12:13], v[12:13], 0, s[36:37]
	s_add_u32 m0, s28, s26
	s_mov_b64 exec, 0xffff
	global_load_lds_dwordx4 v[14:15], off
	s_mov_b64 exec, -1
	v_lshl_add_u64 v[14:15], v[14:15], 0, s[36:37]
	s_mov_b32 s28, 0x12000
	s_add_u32 m0, s28, s24
	s_nop 0
	global_load_lds_dwordx4 v[10:11], off
	v_lshl_add_u64 v[10:11], v[10:11], 0, s[36:37]
	s_add_u32 m0, s28, s25
	s_nop 0
	global_load_lds_dwordx4 v[12:13], off
	v_lshl_add_u64 v[12:13], v[12:13], 0, s[36:37]
	s_add_u32 m0, s28, s26
	s_mov_b64 exec, 0xffff
	global_load_lds_dwordx4 v[14:15], off
	s_mov_b64 exec, -1
	v_lshl_add_u64 v[14:15], v[14:15], 0, s[36:37]
	v_mov_b32_e32 v32, 0
	v_mov_b32_e32 v33, 0
	v_mov_b32_e32 v34, 0
	v_mov_b32_e32 v35, 0
	v_mov_b32_e32 v36, 0
	v_mov_b32_e32 v37, 0
	v_mov_b32_e32 v38, 0
	v_mov_b32_e32 v39, 0
	v_mov_b32_e32 v40, 0
	v_mov_b32_e32 v41, 0
	v_mov_b32_e32 v42, 0
	v_mov_b32_e32 v43, 0
	v_mov_b32_e32 v44, 0
	v_mov_b32_e32 v45, 0
	v_mov_b32_e32 v46, 0
	v_mov_b32_e32 v47, 0
	s_mov_b32 s28, 0x16800
	s_mov_b32 s30, 0
	s_mov_b32 s14, 0

;     DI bool next(int i, Unit& u) const {
;         const long L = (long)i * G + c; if (L >= nwg) return false;
;         int wgid = (int)L; { const int q = nwg / NXCD, r = nwg % NXCD, xcd = wgid % NXCD, off = wgid / NXCD; wgid = (xcd < r ? xcd * (q + 1) : r * (q + 1) + (xcd - r) * q) + off; }
;         const int nig = WGM * nN, gid = wgid / nig, fm = gid * WGM, gsz = (nM - fm) < WGM ? (nM - fm) : WGM;
;         u.pm = fm + ((wgid % nig) % gsz); u.pn = (wgid % nig) / gsz; return true;
;     }
.Ltaild2_0_skip:
	s_cmp_lg_u32 s100, 0
	s_and_b64 vcc, exec, s[6:7]
	v_add_u32_e32 v0, s33, v8
	s_nop 0
	v_readfirstlane_b32 s8, v0
	s_cbranch_vccnz .LBB0_1611
	s_lshr_b32 s9, s3, 29
	s_add_i32 s9, s2, s9
	s_and_b32 s10, s9, -8
	s_sub_i32 s10, s2, s10
	s_cmp_gt_i32 s10, 3
	s_cbranch_scc0 .LBB0_1590
	s_mul_i32 s11, s10, 0xa1
	s_add_i32 s11, s11, 4
	s_cbranch_execz .LBB0_1591
	s_branch .LBB0_1592

; #define PG8_STAGE(bufoff, gbase, voff) do { _Pragma("unroll") for (int _i = 0; _i < 2; ++_i) \
;         __builtin_amdgcn_global_load_lds((const unsigned*)((const char*)(gbase) + (voff)[_i]), (LAS unsigned*)(lds + (bufoff) + ldsw + _i * 8192), 16, 0, 0); } while (0)
; #define PG8_WAIT_V(n) asm volatile("s_waitcnt vmcnt(" #n ")" ::: "memory")
; #define PG8_BAR __builtin_amdgcn_s_barrier()
;     DI bool next(int i, Unit& u) const {
;         const long L = (long)i * G + c; if (L >= nwg) return false;
;         int wgid = (int)L; { const int q = nwg / NXCD, r = nwg % NXCD, xcd = wgid % NXCD, off = wgid / NXCD; wgid = (xcd < r ? xcd * (q + 1) : r * (q + 1) + (xcd - r) * q) + off; }
; template <class Epi>
; DI void gemm_phase(int wv, LAS unsigned char* lds, const Gemm g, const StaticOrder& S, const Epi& E) {
;     ...
;     const char* cA = (const char*)g.A + (size_t)cur.pm * tstep; const char* cB = (const char*)g.Bt + (size_t)cur.pn * tstep;
;     PG8_STAGE(PG8_SB(0, 0), cB, voffB); PG8_STAGE(PG8_SA(0, 0), cA, voffA); PG8_STAGE(PG8_SB(0, 1), cB + hstep, voffB); PG8_STAGE(PG8_SA(0, 1), cA + hstep, voffA);
;     if (wr == 1) PG8_BAR;
;     PG8_WAIT_V(4); PG8_BAR;
;     PG8_STAGE(PG8_SB(1, 0), cB + kstep, voffB); PG8_STAGE(PG8_SA(1, 0), cA + kstep, voffA); PG8_STAGE(PG8_SB(1, 1), cB + hstep + kstep, voffB);
;     PG8_WAIT_V(6); PG8_BAR;
.LBB0_1594:
	s_lshl_b32 s20, s18, 6
	s_lshl_b32 s21, s18, 13
	s_lshl_b32 s18, s19, 5
	s_mov_b64 s[28:29], 0x80
	s_and_b32 s24, s18, 0x60
	s_add_i32 m0, s41, 0x18000
	v_lshl_add_u64 v[6:7], v[6:7], 0, s[28:29]
	s_lshl_b32 s31, s24, 7
	s_waitcnt vmcnt(4)
	s_barrier
	global_load_lds_dwordx4 v[6:7], off
	v_lshl_add_u64 v[4:5], v[4:5], 0, s[28:29]
	s_add_i32 m0, s41, 0x1a000
	s_add_i32 s60, s41, 0x8000
	s_add_i32 s61, s41, 0xa000
	global_load_lds_dwordx4 v[4:5], off
	v_lshl_add_u64 v[2:3], v[2:3], 0, s[28:29]
	s_mov_b32 m0, s60
	s_add_u32 s18, s54, 0xb0080
	global_load_lds_dwordx4 v[2:3], off
	v_lshl_add_u64 v[0:1], v[0:1], 0, s[28:29]
	s_mov_b32 m0, s61
	s_addc_u32 s19, s55, 0
	global_load_lds_dwordx4 v[0:1], off
	s_add_i32 m0, s41, 0x1c000
	v_lshl_add_u64 v[0:1], s[18:19], 0, v[128:129]
	global_load_lds_dwordx4 v[0:1], off
	v_lshl_add_u64 v[0:1], s[18:19], 0, v[130:131]
	s_add_i32 m0, s41, 0x1e000
	v_bfe_u32 v2, v8, 4, 2
	global_load_lds_dwordx4 v[0:1], off
	v_and_b32_e32 v0, 15, v8
	v_lshlrev_b32_e32 v1, 4, v2
	v_lshlrev_b32_e32 v3, 2, v8
	s_sext_i32_i8 s73, s16
	v_lshl_or_b32 v1, v0, 6, v1
	v_and_b32_e32 v3, 32, v3
	s_ashr_i32 s16, s20, 31
	v_bitop3_b32 v4, v1, s21, v3 bitop3:0xde
	v_bitop3_b32 v146, v1, s31, v3 bitop3:0xde
	v_or_b32_e32 v0, s20, v0
	v_mov_b32_e32 v1, s16
	v_lshlrev_b64 v[0:1], 12, v[0:1]
	v_lshl_add_u64 v[134:135], s[26:27], 0, v[0:1]
	v_lshrrev_b32_e32 v1, 1, v9
	v_mul_lo_u32 v0, v11, s17
	s_mov_b32 s16, 0xb000
	v_mad_u64_u32 v[0:1], s[20:21], v1, s16, v[0:1]
	v_or_b32_e32 v0, v0, v10
	v_add_lshl_u32 v132, v0, v12, 1
	v_lshrrev_b32_e32 v1, 1, v13
	v_mul_lo_u32 v0, v14, s17
	v_mad_u64_u32 v[0:1], s[16:17], v1, s16, v[0:1]
	s_mov_b64 s[18:19], 0xb0080
	s_waitcnt vmcnt(6)
	v_or_b32_e32 v0, v0, v15
	v_lshlrev_b32_e32 v2, 2, v2
	v_lshl_add_u64 v[136:137], v[132:133], 0, s[18:19]
	v_add_lshl_u32 v132, v0, v16, 1
	s_add_i32 s62, 0, 0x10000
	s_add_i32 s63, 0, 0x14000
	v_lshl_add_u64 v[138:139], v[132:133], 0, s[18:19]
	v_mov_b64_e32 v[140:141], 0x500
	v_mov_b64_e32 v[142:143], 0x4ff
	v_add_u32_e32 v147, s62, v146
	v_add_u32_e32 v148, 0, v4
	v_add_u32_e32 v149, s63, v146
	s_lshl_b32 s24, s24, 2
	v_lshlrev_b32_e32 v132, 2, v2
	s_mov_b32 s64, 0x20000
	s_mov_b32 s65, 0x30000
	s_mov_b64 s[26:27], 0x80000
	s_mov_b32 s66, 0x80000
	s_mov_b32 s67, 0x90000
	s_mov_b32 s68, 0xa0000
	s_mov_b32 s69, 0xb0000
	s_mov_b32 s70, s25
	s_barrier

; #define LAS __attribute__((address_space(3)))
;     DI bool next(int i, Unit& u) const {
;         const long L = (long)i * G + c; if (L >= nwg) return false;
;         int wgid = (int)L; { const int q = nwg / NXCD, r = nwg % NXCD, xcd = wgid % NXCD, off = wgid / NXCD; wgid = (xcd < r ? xcd * (q + 1) : r * (q + 1) + (xcd - r) * q) + off; }
;         const int nig = WGM * nN, gid = wgid / nig, fm = gid * WGM, gsz = (nM - fm) < WGM ? (nM - fm) : WGM;
;         u.pm = fm + ((wgid % nig) % gsz); u.pn = (wgid % nig) / gsz; return true;
;     }
; template <class Epi>
; DI void gemm_phase(int wv, LAS unsigned char* lds, const Gemm g, const StaticOrder& S, const Epi& E) {
;     const int tid = tid_(wv), wid = __builtin_amdgcn_readfirstlane(tid >> 6), lane = tid & 63, wr = wid >> 2, wc = wid & 3, fr = lane & 15, fq = lane >> 4;
;     const int K = g.K, nt = K / BK;
;     unsigned voffA[2], voffB[2];
; #pragma unroll
;     for (int i = 0; i < 2; ++i) { int R, C; stage_rc(tid * 16 + i * 8192, R, C); const int Rb = Epi::PERM ? ((R & ~31) + perm32(R & 31)) : R; voffA[i] = (unsigned)(R * K + C) * 2u; voffB[i] = (unsigned)(Rb * K + C) * 2u; }
;     const size_t kstep = (size_t)(BK * 2);
;     const size_t hstep = (size_t)HALF * K * 2;
;     const size_t tstep = 2 * hstep;
;     const unsigned ldsw = (unsigned)wid * 1024u;
;     const int aoff = lds_byte(wr * 64 + fr, fq * 8), boff = lds_byte(wc * 32 + fr, fq * 8);
.LBB0_1935:
	s_or_b64 exec, exec, s[14:15]
	v_mov_b32_e32 v8, v254
	s_waitcnt lgkmcnt(0)
	s_barrier
	s_cselect_b32 s100, 1, 0
	s_cmpk_gt_u32 s2, 0xbf
	s_cbranch_scc1 .Ltaild1_1_skip
	v_writelane_b32 v255, s4, 17
	v_writelane_b32 v255, s5, 18
	v_writelane_b32 v255, s6, 19
	v_writelane_b32 v255, s7, 20
	v_writelane_b32 v255, s8, 21
	v_writelane_b32 v255, s9, 22
	v_writelane_b32 v255, s10, 23
	v_writelane_b32 v255, s11, 24
	v_writelane_b32 v255, s12, 25
	v_writelane_b32 v255, s13, 26
	v_writelane_b32 v255, s14, 27
	v_writelane_b32 v255, s15, 28
	v_writelane_b32 v255, s16, 29
	v_writelane_b32 v255, s17, 30
	v_writelane_b32 v255, s18, 31
	v_writelane_b32 v255, s19, 32
	v_writelane_b32 v255, s20, 33
	v_writelane_b32 v255, s21, 34
	v_writelane_b32 v255, s22, 35
	v_writelane_b32 v255, s23, 36
	v_writelane_b32 v255, s24, 37
	v_writelane_b32 v255, s25, 38
	v_writelane_b32 v255, s26, 39
	v_writelane_b32 v255, s27, 40
	v_writelane_b32 v255, s28, 41
	v_writelane_b32 v255, s29, 42
	v_writelane_b32 v255, s30, 43
	v_writelane_b32 v255, s31, 44
	v_writelane_b32 v255, s36, 45
	v_writelane_b32 v255, s37, 46
	v_writelane_b32 v255, s38, 47
	v_writelane_b32 v255, s39, 48
	v_writelane_b32 v255, s40, 49
	v_writelane_b32 v255, s41, 50
	v_writelane_b32 v255, s42, 51
	v_writelane_b32 v255, s43, 52
	v_writelane_b32 v255, s44, 53
	v_writelane_b32 v255, s45, 54
	v_writelane_b32 v255, s46, 55
	v_writelane_b32 v255, s47, 56
	v_writelane_b32 v255, s48, 57
	v_writelane_b32 v255, s49, 58
	v_writelane_b32 v255, s50, 59
	v_writelane_b32 v255, s51, 60
	s_mov_b32 s98, m0
	s_and_b32 s4, s2, 7
	s_lshr_b32 s5, s2, 3
	s_and_b32 s6, s5, 3
	s_lshr_b32 s5, s5, 2
	s_lshl_b32 s5, s5, 3
	s_add_u32 s5, s5, s4
	s_and_b32 s7, s5, 3
	s_lshr_b32 s8, s5, 2
	s_mov_b32 s9, 0x28
	s_cmp_eq_u32 s8, 1
	s_cselect_b32 s9, 0x52, s9
	s_cmp_eq_u32 s8, 2
	s_cselect_b32 s9, 0x7c, s9
	s_cmp_eq_u32 s8, 3
	s_cselect_b32 s9, 0xa6, s9
	s_cmp_eq_u32 s8, 4
	s_cselect_b32 s9, 0x2c8, s9
	s_cmp_eq_u32 s8, 5
	s_cselect_b32 s9, 0x2f1, s9
	s_cmp_eq_u32 s8, 6
	s_cselect_b32 s9, 0x31a, s9
	s_cmp_eq_u32 s8, 7
	s_cselect_b32 s9, 0x742, s9
	s_cmp_eq_u32 s8, 8
	s_cselect_b32 s9, 0x29, s9
	s_cmp_eq_u32 s8, 9
	s_cselect_b32 s9, 0x53, s9
	s_cmp_eq_u32 s8, 10
	s_cselect_b32 s9, 0x7d, s9
	s_cmp_eq_u32 s8, 11
	s_cselect_b32 s9, 0xa7, s9
	s_and_b32 s10, s9, 0x1ff
	s_lshr_b32 s11, s9, 9
	s_lshl_b32 s12, s10, 8
	s_lshl_b32 s4, s7, 6
	s_add_u32 s12, s12, s4
	s_lshl_b32 s13, s11, 8
	s_lshl_b32 s4, s6, 6
	s_add_u32 s13, s13, s4
	s_mul_i32 s4, s12, 0x1600
	s_add_u32 s4, s4, 0x19548000
	s_add_u32 s16, s34, s4
	s_addc_u32 s17, s35, 0
	s_mul_i32 s4, s13, 0x1600
	s_add_u32 s4, s4, 0x17720000
	s_add_u32 s18, s34, s4
	s_addc_u32 s19, s35, 0
	s_lshl_b32 s4, s12, 12
	s_lshl_b32 s5, s13, 2
	s_add_u32 s4, s4, s5
	s_add_u32 s20, s34, s4
	s_addc_u32 s21, s35, 0
	s_lshr_b32 s15, s33, 6
	s_and_b32 s27, s15, 1
	s_bfe_u32 s29, s15, 0x10001
	s_lshr_b32 s31, s15, 2
	v_and_b32_e32 v0, 31, v254
	v_lshrrev_b32_e32 v1, 5, v254
	v_mul_u32_u24_e32 v2, 0x90, v0
	v_lshl_add_u32 v2, v1, 4, v2
	s_mul_i32 s4, s27, 0x1200
	s_lshl_b32 s5, s31, 6
	s_add_u32 s4, s4, s5
	s_mul_i32 s6, s29, 0x1200
	s_add_u32 s6, s6, s5
	s_add_u32 s6, s6, 0x2400
	v_add_u32_e32 v3, s6, v2
	v_add_u32_e32 v2, s4, v2
	s_lshl_b32 s4, s27, 17
	s_lshl_b32 s5, s31, 16
	s_add_u32 s4, s4, s5
	s_lshl_b32 s5, s29, 7
	s_add_u32 s4, s4, s5
	v_lshlrev_b32_e32 v4, 14, v1
	v_lshl_add_u32 v4, v0, 2, v4
	v_add_u32_e32 v4, s4, v4
	v_mov_b32_e32 v72, v4
	v_add_u32_e32 v73, 0x1000, v4
	v_add_u32_e32 v74, 0x2000, v4
	v_add_u32_e32 v75, 0x3000, v4
	v_add_u32_e32 v76, 0x8000, v4
	v_add_u32_e32 v77, 0x9000, v4
	v_add_u32_e32 v78, 0xa000, v4
	v_add_u32_e32 v79, 0xb000, v4
	global_load_dword v64, v72, s[20:21]
	global_load_dword v65, v73, s[20:21]
	global_load_dword v66, v74, s[20:21]
	global_load_dword v67, v75, s[20:21]
	global_load_dword v68, v76, s[20:21]
	global_load_dword v69, v77, s[20:21]
	global_load_dword v70, v78, s[20:21]
	global_load_dword v71, v79, s[20:21]
	s_movk_i32 s48, 0x71c8
	s_mov_b32 s7, 0x1600
; #define PG8_STAGE(bufoff, gbase, voff) do { _Pragma("unroll") for (int _i = 0; _i < 2; ++_i) \
;         __builtin_amdgcn_global_load_lds((const unsigned*)((const char*)(gbase) + (voff)[_i]), (LAS unsigned*)(lds + (bufoff) + ldsw + _i * 8192), 16, 0, 0); } while (0)
; #define PG8_WAIT_V(n) asm volatile("s_waitcnt vmcnt(" #n ")" ::: "memory")
; #define PG8_BAR __builtin_amdgcn_s_barrier()
; template <class Epi>
; DI void gemm_phase(int wv, LAS unsigned char* lds, const Gemm g, const StaticOrder& S, const Epi& E) {
;     ...
;     for (int i = 0; i < 2; ++i) { int R, C; stage_rc(tid * 16 + i * 8192, R, C); const int Rb = Epi::PERM ? ((R & ~31) + perm32(R & 31)) : R; voffA[i] = (unsigned)(R * K + C) * 2u; voffB[i] = (unsigned)(Rb * K + C) * 2u; }
;     const size_t kstep = (size_t)(BK * 2);
;     const size_t hstep = (size_t)HALF * K * 2;
;     const size_t tstep = 2 * hstep;
;     const unsigned ldsw = (unsigned)wid * 1024u;
;     const int aoff = lds_byte(wr * 64 + fr, fq * 8), boff = lds_byte(wc * 32 + fr, fq * 8);
;     ...
;     PG8_STAGE(PG8_SB(0, 0), cB, voffB); PG8_STAGE(PG8_SA(0, 0), cA, voffA); PG8_STAGE(PG8_SB(0, 1), cB + hstep, voffB); PG8_STAGE(PG8_SA(0, 1), cA + hstep, voffA);
;     if (wr == 1) PG8_BAR;
;     PG8_WAIT_V(4); PG8_BAR;
;     PG8_STAGE(PG8_SB(1, 0), cB + kstep, voffB); PG8_STAGE(PG8_SA(1, 0), cA + kstep, voffA); PG8_STAGE(PG8_SB(1, 1), cB + hstep + kstep, voffB);
	s_movk_i32 s36, 0x80
	s_mov_b32 s37, 0
	s_lshl_b32 s4, s15, 6
	s_mov_b64 s[42:43], s[16:17]
	s_lshl_b32 s24, s15, 10
	v_add_u32_e32 v5, s4, v254
	v_mul_lo_u32 v6, v5, s48
	v_lshrrev_b32_e32 v6, 18, v6
	v_mul_u32_u24_e32 v7, 9, v6
	v_sub_u32_e32 v5, v5, v7
	v_cmp_ne_u32_e64 s[22:23], 8, v5
	s_nop 1
	v_cndmask_b32_e64 v5, 0, v5, s[22:23]
	v_mul_lo_u32 v6, v6, s7
	v_lshl_add_u32 v10, v5, 4, v6
	v_mov_b32_e32 v11, 0
	v_lshl_add_u64 v[10:11], s[42:43], 0, v[10:11]
	s_lshl_b32 s4, s15, 6
	s_lshl_b32 s25, s15, 10
	s_movk_i32 s5, 0xffc0
	s_cmp_eq_u32 s15, 0
	s_cselect_b32 s5, 0x200, s5
	s_cselect_b32 s42, s16, s18
	s_cselect_b32 s43, s17, s19
	s_add_u32 s4, s4, s5
	s_add_u32 s25, s25, 0x2000
	v_add_u32_e32 v5, s4, v254
	v_mul_lo_u32 v6, v5, s48
	v_lshrrev_b32_e32 v6, 18, v6
	v_mul_u32_u24_e32 v7, 9, v6
	v_sub_u32_e32 v5, v5, v7
	v_cmp_ne_u32_e64 s[22:23], 8, v5
	s_nop 1
	v_cndmask_b32_e64 v5, 0, v5, s[22:23]
	v_mul_lo_u32 v6, v6, s7
	v_lshl_add_u32 v12, v5, 4, v6
	v_mov_b32_e32 v13, 0
	v_lshl_add_u64 v[12:13], s[42:43], 0, v[12:13]
	s_lshl_b32 s4, s15, 4
	s_add_u32 s4, s4, 0x1c0
	s_mov_b64 s[42:43], s[18:19]
	s_lshl_b32 s26, s15, 8
	s_add_u32 s26, s26, 0x4000
	v_add_u32_e32 v5, s4, v254
	v_mul_lo_u32 v6, v5, s48
	v_lshrrev_b32_e32 v6, 18, v6
	v_mul_u32_u24_e32 v7, 9, v6
	v_sub_u32_e32 v5, v5, v7
	v_cmp_ne_u32_e64 s[22:23], 8, v5
	s_nop 1
	v_cndmask_b32_e64 v5, 0, v5, s[22:23]
	v_mul_lo_u32 v6, v6, s7
	v_lshl_add_u32 v14, v5, 4, v6
	v_mov_b32_e32 v15, 0
	v_lshl_add_u64 v[14:15], s[42:43], 0, v[14:15]
	s_mov_b32 s28, 0x0
	s_add_u32 m0, s28, s24
	s_nop 0
	global_load_lds_dwordx4 v[10:11], off
	v_lshl_add_u64 v[10:11], v[10:11], 0, s[36:37]
	s_add_u32 m0, s28, s25
	s_nop 0
	global_load_lds_dwordx4 v[12:13], off
	v_lshl_add_u64 v[12:13], v[12:13], 0, s[36:37]
	s_add_u32 m0, s28, s26
	s_mov_b64 exec, 0xffff
	global_load_lds_dwordx4 v[14:15], off
	s_mov_b64 exec, -1
	v_lshl_add_u64 v[14:15], v[14:15], 0, s[36:37]
	s_mov_b32 s28, 0x4800
	s_add_u32 m0, s28, s24
	s_nop 0
	global_load_lds_dwordx4 v[10:11], off
	v_lshl_add_u64 v[10:11], v[10:11], 0, s[36:37]
	s_add_u32 m0, s28, s25
	s_nop 0
	global_load_lds_dwordx4 v[12:13], off
	v_lshl_add_u64 v[12:13], v[12:13], 0, s[36:37]
	s_add_u32 m0, s28, s26
	s_mov_b64 exec, 0xffff
	global_load_lds_dwordx4 v[14:15], off
	s_mov_b64 exec, -1
	v_lshl_add_u64 v[14:15], v[14:15], 0, s[36:37]
	s_mov_b32 s28, 0x9000
	s_add_u32 m0, s28, s24
	s_nop 0
	global_load_lds_dwordx4 v[10:11], off
	v_lshl_add_u64 v[10:11], v[10:11], 0, s[36:37]
	s_add_u32 m0, s28, s25
	s_nop 0
	global_load_lds_dwordx4 v[12:13], off
	v_lshl_add_u64 v[12:13], v[12:13], 0, s[36:37]
	s_add_u32 m0, s28, s26
	s_mov_b64 exec, 0xffff
	global_load_lds_dwordx4 v[14:15], off
	s_mov_b64 exec, -1
	v_lshl_add_u64 v[14:15], v[14:15], 0, s[36:37]
	s_mov_b32 s28, 0xd800
	s_add_u32 m0, s28, s24
	s_nop 0
	global_load_lds_dwordx4 v[10:11], off
	v_lshl_add_u64 v[10:11], v[10:11], 0, s[36:37]
	s_add_u32 m0, s28, s25
	s_nop 0
	global_load_lds_dwordx4 v[12:13], off
	v_lshl_add_u64 v[12:13], v[12:13], 0, s[36:37]
	s_add_u32 m0, s28, s26
	s_mov_b64 exec, 0xffff
	global_load_lds_dwordx4 v[14:15], off
	s_mov_b64 exec, -1
	v_lshl_add_u64 v[14:15], v[14:15], 0, s[36:37]
	s_mov_b32 s28, 0x12000
	s_add_u32 m0, s28, s24
	s_nop 0
	global_load_lds_dwordx4 v[10:11], off
	v_lshl_add_u64 v[10:11], v[10:11], 0, s[36:37]
	s_add_u32 m0, s28, s25
	s_nop 0
	global_load_lds_dwordx4 v[12:13], off
	v_lshl_add_u64 v[12:13], v[12:13], 0, s[36:37]
	s_add_u32 m0, s28, s26
	s_mov_b64 exec, 0xffff
	global_load_lds_dwordx4 v[14:15], off
	s_mov_b64 exec, -1
	v_lshl_add_u64 v[14:15], v[14:15], 0, s[36:37]
	v_mov_b32_e32 v32, 0
	v_mov_b32_e32 v33, 0
	v_mov_b32_e32 v34, 0
	v_mov_b32_e32 v35, 0
	v_mov_b32_e32 v36, 0
	v_mov_b32_e32 v37, 0
	v_mov_b32_e32 v38, 0
	v_mov_b32_e32 v39, 0
	v_mov_b32_e32 v40, 0
	v_mov_b32_e32 v41, 0
	v_mov_b32_e32 v42, 0
	v_mov_b32_e32 v43, 0
	v_mov_b32_e32 v44, 0
	v_mov_b32_e32 v45, 0
	v_mov_b32_e32 v46, 0
	v_mov_b32_e32 v47, 0
	s_mov_b32 s28, 0x16800
	s_mov_b32 s30, 0
	s_mov_b32 s14, 0

; #define PG8_STAGE(bufoff, gbase, voff) do { _Pragma("unroll") for (int _i = 0; _i < 2; ++_i) \
;         __builtin_amdgcn_global_load_lds((const unsigned*)((const char*)(gbase) + (voff)[_i]), (LAS unsigned*)(lds + (bufoff) + ldsw + _i * 8192), 16, 0, 0); } while (0)
; #define PG8_WAIT_V(n) asm volatile("s_waitcnt vmcnt(" #n ")" ::: "memory")
; #define PG8_BAR __builtin_amdgcn_s_barrier()
;     DI bool next(int i, Unit& u) const {
;         const long L = (long)i * G + c; if (L >= nwg) return false;
;         int wgid = (int)L; { const int q = nwg / NXCD, r = nwg % NXCD, xcd = wgid % NXCD, off = wgid / NXCD; wgid = (xcd < r ? xcd * (q + 1) : r * (q + 1) + (xcd - r) * q) + off; }
; template <class Epi>
; DI void gemm_phase(int wv, LAS unsigned char* lds, const Gemm g, const StaticOrder& S, const Epi& E) {
;     ...
;     const char* cA = (const char*)g.A + (size_t)cur.pm * tstep; const char* cB = (const char*)g.Bt + (size_t)cur.pn * tstep;
;     PG8_STAGE(PG8_SB(0, 0), cB, voffB); PG8_STAGE(PG8_SA(0, 0), cA, voffA); PG8_STAGE(PG8_SB(0, 1), cB + hstep, voffB); PG8_STAGE(PG8_SA(0, 1), cA + hstep, voffA);
;     if (wr == 1) PG8_BAR;
;     PG8_WAIT_V(4); PG8_BAR;
;     PG8_STAGE(PG8_SB(1, 0), cB + kstep, voffB); PG8_STAGE(PG8_SA(1, 0), cA + kstep, voffA); PG8_STAGE(PG8_SB(1, 1), cB + hstep + kstep, voffB);
;     PG8_WAIT_V(6); PG8_BAR;
.LBB0_1942:
	s_lshl_b32 s18, s16, 6
	s_lshl_b32 s19, s16, 13
	s_lshl_b32 s16, s17, 5
	s_mov_b64 s[26:27], 0x80
	s_and_b32 s24, s16, 0x60
	s_add_i32 m0, s41, 0x18000
	v_lshl_add_u64 v[6:7], v[6:7], 0, s[26:27]
	s_lshl_b32 s28, s24, 7
	s_waitcnt vmcnt(4)
	s_barrier
	global_load_lds_dwordx4 v[6:7], off
	v_lshl_add_u64 v[4:5], v[4:5], 0, s[26:27]
	s_add_i32 m0, s41, 0x1a000
	s_add_i32 s62, s41, 0x8000
	s_add_i32 s63, s41, 0xa000
	global_load_lds_dwordx4 v[4:5], off
	v_lshl_add_u64 v[2:3], v[2:3], 0, s[26:27]
	s_mov_b32 m0, s62
	s_add_u32 s16, s54, 0xb0080
	global_load_lds_dwordx4 v[2:3], off
	v_lshl_add_u64 v[0:1], v[0:1], 0, s[26:27]
	s_mov_b32 m0, s63
	s_addc_u32 s17, s55, 0
	global_load_lds_dwordx4 v[0:1], off
	s_add_i32 m0, s41, 0x1c000
	v_lshl_add_u64 v[0:1], s[16:17], 0, v[128:129]
	global_load_lds_dwordx4 v[0:1], off
	v_lshl_add_u64 v[0:1], s[16:17], 0, v[130:131]
	s_add_i32 m0, s41, 0x1e000
	v_bfe_u32 v2, v8, 4, 2
	global_load_lds_dwordx4 v[0:1], off
	v_and_b32_e32 v0, 15, v8
	v_lshlrev_b32_e32 v1, 4, v2
	v_lshlrev_b32_e32 v3, 2, v8
	s_sext_i32_i8 s75, s14
	v_lshl_or_b32 v1, v0, 6, v1
	v_and_b32_e32 v3, 32, v3
	s_ashr_i32 s14, s18, 31
	v_bitop3_b32 v4, v1, s19, v3 bitop3:0xde
	v_bitop3_b32 v146, v1, s28, v3 bitop3:0xde
	v_or_b32_e32 v0, s18, v0
	v_mov_b32_e32 v1, s14
	v_lshlrev_b64 v[0:1], 12, v[0:1]
	v_lshl_add_u64 v[134:135], s[22:23], 0, v[0:1]
	v_lshrrev_b32_e32 v1, 1, v9
	v_mul_lo_u32 v0, v11, s15
	s_mov_b32 s14, 0xb000
	v_mad_u64_u32 v[0:1], s[18:19], v1, s14, v[0:1]
	v_or_b32_e32 v0, v0, v10
	v_add_lshl_u32 v132, v0, v12, 1
	v_lshrrev_b32_e32 v1, 1, v13
	v_mul_lo_u32 v0, v14, s15
	v_mad_u64_u32 v[0:1], s[14:15], v1, s14, v[0:1]
	s_mov_b64 s[16:17], 0xb0080
	s_waitcnt vmcnt(6)
	v_or_b32_e32 v0, v0, v15
	v_lshlrev_b32_e32 v2, 2, v2
	v_lshl_add_u64 v[136:137], v[132:133], 0, s[16:17]
	v_add_lshl_u32 v132, v0, v16, 1
	s_add_i32 s64, 0, 0x10000
	s_add_i32 s65, 0, 0x14000
	v_lshl_add_u64 v[138:139], v[132:133], 0, s[16:17]
	v_mov_b64_e32 v[140:141], 0x500
	v_mov_b64_e32 v[142:143], 0x4ff
	v_add_u32_e32 v147, s64, v146
	v_add_u32_e32 v148, 0, v4
	v_add_u32_e32 v149, s65, v146
	s_lshl_b32 s24, s24, 2
	v_lshlrev_b32_e32 v132, 2, v2
	s_mov_b32 s66, 0x20000
	s_mov_b32 s67, 0x30000
	s_mov_b64 s[28:29], 0x80000
	s_mov_b32 s68, 0x80000
	s_mov_b32 s69, 0x90000
	s_mov_b32 s70, 0xa0000
	s_mov_b32 s71, 0xb0000
	s_mov_b32 s72, s25
	s_barrier

; #define LAS __attribute__((address_space(3)))
;     DI bool next(int i, Unit& u) const {
;         const long L = (long)i * G + c; if (L >= nwg) return false;
;         int wgid = (int)L; { const int q = nwg / NXCD, r = nwg % NXCD, xcd = wgid % NXCD, off = wgid / NXCD; wgid = (xcd < r ? xcd * (q + 1) : r * (q + 1) + (xcd - r) * q) + off; }
;         const int nig = WGM * nN, gid = wgid / nig, fm = gid * WGM, gsz = (nM - fm) < WGM ? (nM - fm) : WGM;
;         u.pm = fm + ((wgid % nig) % gsz); u.pn = (wgid % nig) / gsz; return true;
;     }
; template <class Epi>
; DI void gemm_phase(int wv, LAS unsigned char* lds, const Gemm g, const StaticOrder& S, const Epi& E) {
;     const int tid = tid_(wv), wid = __builtin_amdgcn_readfirstlane(tid >> 6), lane = tid & 63, wr = wid >> 2, wc = wid & 3, fr = lane & 15, fq = lane >> 4;
;     const int K = g.K, nt = K / BK;
;     unsigned voffA[2], voffB[2];
; #pragma unroll
;     for (int i = 0; i < 2; ++i) { int R, C; stage_rc(tid * 16 + i * 8192, R, C); const int Rb = Epi::PERM ? ((R & ~31) + perm32(R & 31)) : R; voffA[i] = (unsigned)(R * K + C) * 2u; voffB[i] = (unsigned)(Rb * K + C) * 2u; }
;     const size_t kstep = (size_t)(BK * 2);
;     const size_t hstep = (size_t)HALF * K * 2;
;     const size_t tstep = 2 * hstep;
;     const unsigned ldsw = (unsigned)wid * 1024u;
;     const int aoff = lds_byte(wr * 64 + fr, fq * 8), boff = lds_byte(wc * 32 + fr, fq * 8);
.LBB0_2993:
	s_or_b64 exec, exec, s[4:5]
	v_mov_b32_e32 v8, v254
	s_waitcnt lgkmcnt(0)
	s_barrier
	s_cselect_b32 s100, 1, 0
	s_cmpk_gt_u32 s2, 0xbf
	s_cbranch_scc1 .Ltailout_1_skip
	v_writelane_b32 v255, s4, 17
	v_writelane_b32 v255, s5, 18
	v_writelane_b32 v255, s6, 19
	v_writelane_b32 v255, s7, 20
	v_writelane_b32 v255, s8, 21
	v_writelane_b32 v255, s9, 22
	v_writelane_b32 v255, s10, 23
	v_writelane_b32 v255, s11, 24
	v_writelane_b32 v255, s12, 25
	v_writelane_b32 v255, s13, 26
	v_writelane_b32 v255, s14, 27
	v_writelane_b32 v255, s15, 28
	v_writelane_b32 v255, s16, 29
	v_writelane_b32 v255, s17, 30
	v_writelane_b32 v255, s18, 31
	v_writelane_b32 v255, s19, 32
	v_writelane_b32 v255, s20, 33
	v_writelane_b32 v255, s21, 34
	v_writelane_b32 v255, s22, 35
	v_writelane_b32 v255, s23, 36
	v_writelane_b32 v255, s24, 37
	v_writelane_b32 v255, s25, 38
	v_writelane_b32 v255, s26, 39
	v_writelane_b32 v255, s27, 40
	v_writelane_b32 v255, s28, 41
	v_writelane_b32 v255, s29, 42
	v_writelane_b32 v255, s30, 43
	v_writelane_b32 v255, s31, 44
	v_writelane_b32 v255, s36, 45
	v_writelane_b32 v255, s37, 46
	v_writelane_b32 v255, s38, 47
	v_writelane_b32 v255, s39, 48
	v_writelane_b32 v255, s40, 49
	v_writelane_b32 v255, s41, 50
	v_writelane_b32 v255, s42, 51
	v_writelane_b32 v255, s43, 52
	v_writelane_b32 v255, s44, 53
	v_writelane_b32 v255, s45, 54
	v_writelane_b32 v255, s46, 55
	v_writelane_b32 v255, s47, 56
	v_writelane_b32 v255, s48, 57
	v_writelane_b32 v255, s49, 58
	v_writelane_b32 v255, s50, 59
	v_writelane_b32 v255, s51, 60
	s_mov_b32 s98, m0
	s_and_b32 s4, s2, 7
	s_lshr_b32 s5, s2, 3
	s_and_b32 s6, s5, 3
	s_lshr_b32 s5, s5, 2
	s_lshl_b32 s5, s5, 3
	s_add_u32 s5, s5, s4
	s_and_b32 s7, s5, 3
	s_lshr_b32 s8, s5, 2
	s_mov_b32 s9, 0x28
	s_cmp_eq_u32 s8, 1
	s_cselect_b32 s9, 0x52, s9
	s_cmp_eq_u32 s8, 2
	s_cselect_b32 s9, 0x7c, s9
	s_cmp_eq_u32 s8, 3
	s_cselect_b32 s9, 0xa6, s9
	s_cmp_eq_u32 s8, 4
	s_cselect_b32 s9, 0x2c8, s9
	s_cmp_eq_u32 s8, 5
	s_cselect_b32 s9, 0x2f1, s9
	s_cmp_eq_u32 s8, 6
	s_cselect_b32 s9, 0x31a, s9
	s_cmp_eq_u32 s8, 7
	s_cselect_b32 s9, 0x742, s9
	s_cmp_eq_u32 s8, 8
	s_cselect_b32 s9, 0x29, s9
	s_cmp_eq_u32 s8, 9
	s_cselect_b32 s9, 0x53, s9
	s_cmp_eq_u32 s8, 10
	s_cselect_b32 s9, 0x7d, s9
	s_cmp_eq_u32 s8, 11
	s_cselect_b32 s9, 0xa7, s9
	s_and_b32 s10, s9, 0x1ff
	s_lshr_b32 s11, s9, 9
	s_lshl_b32 s12, s10, 8
	s_lshl_b32 s4, s7, 6
	s_add_u32 s12, s12, s4
	s_lshl_b32 s13, s11, 8
	s_lshl_b32 s4, s6, 6
	s_add_u32 s13, s13, s4
	s_mul_i32 s4, s12, 0x800
	s_add_u32 s4, s4, 0x19548000
	s_add_u32 s16, s34, s4
	s_addc_u32 s17, s35, 0
	s_mul_i32 s4, s13, 0x800
	s_add_u32 s4, s4, 0x19340000
	s_add_u32 s18, s34, s4
	s_addc_u32 s19, s35, 0
	s_lshl_b32 s4, s12, 12
	s_lshl_b32 s5, s13, 2
	s_add_u32 s4, s4, s5
	s_add_u32 s20, s34, s4
	s_addc_u32 s21, s35, 0
	s_lshr_b32 s15, s33, 6
	s_and_b32 s27, s15, 1
	s_bfe_u32 s29, s15, 0x10001
	s_lshr_b32 s31, s15, 2
	v_and_b32_e32 v0, 31, v254
	v_lshrrev_b32_e32 v1, 5, v254
	v_mul_u32_u24_e32 v2, 0x90, v0
	v_lshl_add_u32 v2, v1, 4, v2
	s_mul_i32 s4, s27, 0x1200
	s_lshl_b32 s5, s31, 6
	s_add_u32 s4, s4, s5
	s_mul_i32 s6, s29, 0x1200
	s_add_u32 s6, s6, s5
	s_add_u32 s6, s6, 0x2400
	v_add_u32_e32 v3, s6, v2
	v_add_u32_e32 v2, s4, v2
	s_lshl_b32 s4, s27, 17
	s_lshl_b32 s5, s31, 16
	s_add_u32 s4, s4, s5
	s_lshl_b32 s5, s29, 7
	s_add_u32 s4, s4, s5
	v_lshlrev_b32_e32 v4, 14, v1
	v_lshl_add_u32 v4, v0, 2, v4
	v_add_u32_e32 v4, s4, v4
	v_mov_b32_e32 v72, v4
	v_add_u32_e32 v73, 0x1000, v4
	v_add_u32_e32 v74, 0x2000, v4
	v_add_u32_e32 v75, 0x3000, v4
	v_add_u32_e32 v76, 0x8000, v4
	v_add_u32_e32 v77, 0x9000, v4
	v_add_u32_e32 v78, 0xa000, v4
	v_add_u32_e32 v79, 0xb000, v4
	global_load_dword v64, v72, s[20:21]
	global_load_dword v65, v73, s[20:21]
	global_load_dword v66, v74, s[20:21]
	global_load_dword v67, v75, s[20:21]
	global_load_dword v68, v76, s[20:21]
	global_load_dword v69, v77, s[20:21]
	global_load_dword v70, v78, s[20:21]
	global_load_dword v71, v79, s[20:21]
	s_movk_i32 s48, 0x71c8
	s_mov_b32 s7, 0x800
; #define PG8_STAGE(bufoff, gbase, voff) do { _Pragma("unroll") for (int _i = 0; _i < 2; ++_i) \
;         __builtin_amdgcn_global_load_lds((const unsigned*)((const char*)(gbase) + (voff)[_i]), (LAS unsigned*)(lds + (bufoff) + ldsw + _i * 8192), 16, 0, 0); } while (0)
; #define PG8_WAIT_V(n) asm volatile("s_waitcnt vmcnt(" #n ")" ::: "memory")
; #define PG8_BAR __builtin_amdgcn_s_barrier()
; template <class Epi>
; DI void gemm_phase(int wv, LAS unsigned char* lds, const Gemm g, const StaticOrder& S, const Epi& E) {
;     ...
;     for (int i = 0; i < 2; ++i) { int R, C; stage_rc(tid * 16 + i * 8192, R, C); const int Rb = Epi::PERM ? ((R & ~31) + perm32(R & 31)) : R; voffA[i] = (unsigned)(R * K + C) * 2u; voffB[i] = (unsigned)(Rb * K + C) * 2u; }
;     const size_t kstep = (size_t)(BK * 2);
;     const size_t hstep = (size_t)HALF * K * 2;
;     const size_t tstep = 2 * hstep;
;     const unsigned ldsw = (unsigned)wid * 1024u;
;     const int aoff = lds_byte(wr * 64 + fr, fq * 8), boff = lds_byte(wc * 32 + fr, fq * 8);
;     ...
;     PG8_STAGE(PG8_SB(0, 0), cB, voffB); PG8_STAGE(PG8_SA(0, 0), cA, voffA); PG8_STAGE(PG8_SB(0, 1), cB + hstep, voffB); PG8_STAGE(PG8_SA(0, 1), cA + hstep, voffA);
;     if (wr == 1) PG8_BAR;
;     PG8_WAIT_V(4); PG8_BAR;
;     PG8_STAGE(PG8_SB(1, 0), cB + kstep, voffB); PG8_STAGE(PG8_SA(1, 0), cA + kstep, voffA); PG8_STAGE(PG8_SB(1, 1), cB + hstep + kstep, voffB);
	s_movk_i32 s36, 0x80
	s_mov_b32 s37, 0
	s_lshl_b32 s4, s15, 6
	s_mov_b64 s[42:43], s[16:17]
	s_lshl_b32 s24, s15, 10
	v_add_u32_e32 v5, s4, v254
	v_mul_lo_u32 v6, v5, s48
	v_lshrrev_b32_e32 v6, 18, v6
	v_mul_u32_u24_e32 v7, 9, v6
	v_sub_u32_e32 v5, v5, v7
	v_cmp_ne_u32_e64 s[22:23], 8, v5
	s_nop 1
	v_cndmask_b32_e64 v5, 0, v5, s[22:23]
	v_mul_lo_u32 v6, v6, s7
	v_lshl_add_u32 v10, v5, 4, v6
	v_mov_b32_e32 v11, 0
	v_lshl_add_u64 v[10:11], s[42:43], 0, v[10:11]
	s_lshl_b32 s4, s15, 6
	s_lshl_b32 s25, s15, 10
	s_movk_i32 s5, 0xffc0
	s_cmp_eq_u32 s15, 0
	s_cselect_b32 s5, 0x200, s5
	s_cselect_b32 s42, s16, s18
	s_cselect_b32 s43, s17, s19
	s_add_u32 s4, s4, s5
	s_add_u32 s25, s25, 0x2000
	v_add_u32_e32 v5, s4, v254
	v_mul_lo_u32 v6, v5, s48
	v_lshrrev_b32_e32 v6, 18, v6
	v_mul_u32_u24_e32 v7, 9, v6
	v_sub_u32_e32 v5, v5, v7
	v_cmp_ne_u32_e64 s[22:23], 8, v5
	s_nop 1
	v_cndmask_b32_e64 v5, 0, v5, s[22:23]
	v_mul_lo_u32 v6, v6, s7
	v_lshl_add_u32 v12, v5, 4, v6
	v_mov_b32_e32 v13, 0
	v_lshl_add_u64 v[12:13], s[42:43], 0, v[12:13]
	s_lshl_b32 s4, s15, 4
	s_add_u32 s4, s4, 0x1c0
	s_mov_b64 s[42:43], s[18:19]
	s_lshl_b32 s26, s15, 8
	s_add_u32 s26, s26, 0x4000
	v_add_u32_e32 v5, s4, v254
	v_mul_lo_u32 v6, v5, s48
	v_lshrrev_b32_e32 v6, 18, v6
	v_mul_u32_u24_e32 v7, 9, v6
	v_sub_u32_e32 v5, v5, v7
	v_cmp_ne_u32_e64 s[22:23], 8, v5
	s_nop 1
	v_cndmask_b32_e64 v5, 0, v5, s[22:23]
	v_mul_lo_u32 v6, v6, s7
	v_lshl_add_u32 v14, v5, 4, v6
	v_mov_b32_e32 v15, 0
	v_lshl_add_u64 v[14:15], s[42:43], 0, v[14:15]
	s_mov_b32 s28, 0x0
	s_add_u32 m0, s28, s24
	s_nop 0
	global_load_lds_dwordx4 v[10:11], off
	v_lshl_add_u64 v[10:11], v[10:11], 0, s[36:37]
	s_add_u32 m0, s28, s25
	s_nop 0
	global_load_lds_dwordx4 v[12:13], off
	v_lshl_add_u64 v[12:13], v[12:13], 0, s[36:37]
	s_add_u32 m0, s28, s26
	s_mov_b64 exec, 0xffff
	global_load_lds_dwordx4 v[14:15], off
	s_mov_b64 exec, -1
	v_lshl_add_u64 v[14:15], v[14:15], 0, s[36:37]
	s_mov_b32 s28, 0x4800
	s_add_u32 m0, s28, s24
	s_nop 0
	global_load_lds_dwordx4 v[10:11], off
	v_lshl_add_u64 v[10:11], v[10:11], 0, s[36:37]
	s_add_u32 m0, s28, s25
	s_nop 0
	global_load_lds_dwordx4 v[12:13], off
	v_lshl_add_u64 v[12:13], v[12:13], 0, s[36:37]
	s_add_u32 m0, s28, s26
	s_mov_b64 exec, 0xffff
	global_load_lds_dwordx4 v[14:15], off
	s_mov_b64 exec, -1
	v_lshl_add_u64 v[14:15], v[14:15], 0, s[36:37]
	s_mov_b32 s28, 0x9000
	s_add_u32 m0, s28, s24
	s_nop 0
	global_load_lds_dwordx4 v[10:11], off
	v_lshl_add_u64 v[10:11], v[10:11], 0, s[36:37]
	s_add_u32 m0, s28, s25
	s_nop 0
	global_load_lds_dwordx4 v[12:13], off
	v_lshl_add_u64 v[12:13], v[12:13], 0, s[36:37]
	s_add_u32 m0, s28, s26
	s_mov_b64 exec, 0xffff
	global_load_lds_dwordx4 v[14:15], off
	s_mov_b64 exec, -1
	v_lshl_add_u64 v[14:15], v[14:15], 0, s[36:37]
	s_mov_b32 s28, 0xd800
	s_add_u32 m0, s28, s24
	s_nop 0
	global_load_lds_dwordx4 v[10:11], off
	v_lshl_add_u64 v[10:11], v[10:11], 0, s[36:37]
	s_add_u32 m0, s28, s25
	s_nop 0
	global_load_lds_dwordx4 v[12:13], off
	v_lshl_add_u64 v[12:13], v[12:13], 0, s[36:37]
	s_add_u32 m0, s28, s26
	s_mov_b64 exec, 0xffff
	global_load_lds_dwordx4 v[14:15], off
	s_mov_b64 exec, -1
	v_lshl_add_u64 v[14:15], v[14:15], 0, s[36:37]
	s_mov_b32 s28, 0x12000
	s_add_u32 m0, s28, s24
	s_nop 0
	global_load_lds_dwordx4 v[10:11], off
	v_lshl_add_u64 v[10:11], v[10:11], 0, s[36:37]
	s_add_u32 m0, s28, s25
	s_nop 0
	global_load_lds_dwordx4 v[12:13], off
	v_lshl_add_u64 v[12:13], v[12:13], 0, s[36:37]
	s_add_u32 m0, s28, s26
	s_mov_b64 exec, 0xffff
	global_load_lds_dwordx4 v[14:15], off
	s_mov_b64 exec, -1
	v_lshl_add_u64 v[14:15], v[14:15], 0, s[36:37]
	v_mov_b32_e32 v32, 0
	v_mov_b32_e32 v33, 0
	v_mov_b32_e32 v34, 0
	v_mov_b32_e32 v35, 0
	v_mov_b32_e32 v36, 0
	v_mov_b32_e32 v37, 0
	v_mov_b32_e32 v38, 0
	v_mov_b32_e32 v39, 0
	v_mov_b32_e32 v40, 0
	v_mov_b32_e32 v41, 0
	v_mov_b32_e32 v42, 0
	v_mov_b32_e32 v43, 0
	v_mov_b32_e32 v44, 0
	v_mov_b32_e32 v45, 0
	v_mov_b32_e32 v46, 0
	v_mov_b32_e32 v47, 0
	s_mov_b32 s28, 0x16800
	s_mov_b32 s30, 0
	s_mov_b32 s14, 0

;     DI bool next(int i, Unit& u) const {
;         const long L = (long)i * G + c; if (L >= nwg) return false;
;         int wgid = (int)L; { const int q = nwg / NXCD, r = nwg % NXCD, xcd = wgid % NXCD, off = wgid / NXCD; wgid = (xcd < r ? xcd * (q + 1) : r * (q + 1) + (xcd - r) * q) + off; }
;         const int nig = WGM * nN, gid = wgid / nig, fm = gid * WGM, gsz = (nM - fm) < WGM ? (nM - fm) : WGM;
;         u.pm = fm + ((wgid % nig) % gsz); u.pn = (wgid % nig) / gsz; return true;
;     }
.Ltailout_1_skip:
	s_cmp_lg_u32 s100, 0
	s_and_b64 vcc, exec, s[6:7]
	v_add_u32_e32 v0, s33, v8
	s_nop 0
	v_readfirstlane_b32 s41, v0
	s_cbranch_vccnz .LBB0_3013
	s_load_dwordx2 s[4:5], s[0:1], 0x128
	s_lshr_b32 s8, s3, 29
	s_add_i32 s11, s2, s8
	s_and_b32 s8, s11, -8
	s_sub_i32 s14, s2, s8
	s_cmp_gt_i32 s14, 3
	s_cbranch_scc0 .LBB0_2996
	s_mul_i32 s8, s14, 0xa1
	s_add_i32 s10, s8, 4
	s_cbranch_execz .LBB0_2997
	s_branch .LBB0_2998

; #define PG8_STAGE(bufoff, gbase, voff) do { _Pragma("unroll") for (int _i = 0; _i < 2; ++_i) \
;         __builtin_amdgcn_global_load_lds((const unsigned*)((const char*)(gbase) + (voff)[_i]), (LAS unsigned*)(lds + (bufoff) + ldsw + _i * 8192), 16, 0, 0); } while (0)
; #define PG8_WAIT_V(n) asm volatile("s_waitcnt vmcnt(" #n ")" ::: "memory")
; #define PG8_BAR __builtin_amdgcn_s_barrier()
;     DI bool next(int i, Unit& u) const {
;         const long L = (long)i * G + c; if (L >= nwg) return false;
;         int wgid = (int)L; { const int q = nwg / NXCD, r = nwg % NXCD, xcd = wgid % NXCD, off = wgid / NXCD; wgid = (xcd < r ? xcd * (q + 1) : r * (q + 1) + (xcd - r) * q) + off; }
; template <class Epi>
; DI void gemm_phase(int wv, LAS unsigned char* lds, const Gemm g, const StaticOrder& S, const Epi& E) {
;     ...
;     const char* cA = (const char*)g.A + (size_t)cur.pm * tstep; const char* cB = (const char*)g.Bt + (size_t)cur.pn * tstep;
;     PG8_STAGE(PG8_SB(0, 0), cB, voffB); PG8_STAGE(PG8_SA(0, 0), cA, voffA); PG8_STAGE(PG8_SB(0, 1), cB + hstep, voffB); PG8_STAGE(PG8_SA(0, 1), cA + hstep, voffA);
;     if (wr == 1) PG8_BAR;
;     PG8_WAIT_V(4); PG8_BAR;
;     PG8_STAGE(PG8_SB(1, 0), cB + kstep, voffB); PG8_STAGE(PG8_SA(1, 0), cA + kstep, voffA); PG8_STAGE(PG8_SB(1, 1), cB + hstep + kstep, voffB);
;     PG8_WAIT_V(6); PG8_BAR;
.LBB0_3000:
	s_lshl_b32 s8, s8, 5
	s_mov_b64 s[10:11], 0x80
	s_and_b32 s8, s8, 0x60
	s_add_i32 m0, s55, 0x18000
	v_lshl_add_u64 v[6:7], v[6:7], 0, s[10:11]
	s_lshl_b32 s16, s5, 6
	s_lshl_b32 s5, s5, 13
	s_lshl_b32 s17, s8, 7
	s_waitcnt vmcnt(4)
	s_barrier
	global_load_lds_dwordx4 v[6:7], off
	v_lshl_add_u64 v[4:5], v[4:5], 0, s[10:11]
	s_add_i32 m0, s55, 0x1a000
	s_add_i32 s60, s55, 0x8000
	s_add_i32 s61, s55, 0xa000
	global_load_lds_dwordx4 v[4:5], off
	v_lshl_add_u64 v[2:3], v[2:3], 0, s[10:11]
	s_mov_b32 m0, s60
	s_add_u32 s14, s36, 0x40080
	global_load_lds_dwordx4 v[2:3], off
	v_lshl_add_u64 v[0:1], v[0:1], 0, s[10:11]
	s_mov_b32 m0, s61
	s_addc_u32 s15, s37, 0
	global_load_lds_dwordx4 v[0:1], off
	s_add_i32 m0, s55, 0x1c000
	v_lshl_add_u64 v[0:1], s[14:15], 0, v[128:129]
	global_load_lds_dwordx4 v[0:1], off
	v_lshl_add_u64 v[0:1], s[14:15], 0, v[130:131]
	s_add_i32 m0, s55, 0x1e000
	v_bfe_u32 v2, v8, 4, 2
	global_load_lds_dwordx4 v[0:1], off
	v_and_b32_e32 v0, 15, v8
	v_lshlrev_b32_e32 v1, 4, v2
	v_lshlrev_b32_e32 v3, 2, v8
	v_lshl_or_b32 v1, v0, 6, v1
	v_and_b32_e32 v3, 32, v3
	s_ashr_i32 s14, s16, 31
	v_bitop3_b32 v4, v1, s5, v3 bitop3:0xde
	v_bitop3_b32 v146, v1, s17, v3 bitop3:0xde
	v_or_b32_e32 v0, s16, v0
	v_mov_b32_e32 v1, s14
	v_lshlrev_b64 v[0:1], 12, v[0:1]
	v_lshl_add_u64 v[134:135], s[22:23], 0, v[0:1]
	v_lshlrev_b32_e32 v0, 13, v9
	v_and_b32_e32 v0, 0x7fffc000, v0
	v_lshl_add_u32 v0, v10, 10, v0
	v_or_b32_e32 v0, v0, v11
	v_add_lshl_u32 v132, v0, v12, 1
	v_lshlrev_b32_e32 v0, 13, v13
	v_and_b32_e32 v0, 0x7fffc000, v0
	v_lshl_add_u32 v0, v14, 10, v0
	s_sext_i32_i8 s71, s4
	s_mov_b64 s[4:5], 0x40080
	s_waitcnt vmcnt(6)
	v_or_b32_e32 v0, v0, v15
	v_lshlrev_b32_e32 v2, 2, v2
	v_lshl_add_u64 v[136:137], v[132:133], 0, s[4:5]
	v_add_lshl_u32 v132, v0, v16, 1
	s_add_i32 s62, 0, 0x10000
	s_add_i32 s63, 0, 0x14000
	v_lshl_add_u64 v[138:139], v[132:133], 0, s[4:5]
	v_mov_b64_e32 v[140:141], 0x500
	v_mov_b64_e32 v[142:143], 0x4ff
	v_add_u32_e32 v147, s62, v146
	v_add_u32_e32 v148, 0, v4
	v_add_u32_e32 v149, s63, v146
	s_lshl_b32 s8, s8, 2
	v_lshlrev_b32_e32 v132, 2, v2
	s_mov_b32 s64, 0x20000
	s_mov_b32 s65, 0x30000
	s_mov_b64 s[14:15], 0x80000
	s_mov_b32 s66, 0x80000
	s_mov_b32 s67, 0x90000
	s_mov_b32 s68, 0xa0000
	s_mov_b32 s69, 0xb0000
	s_mov_b32 s70, s9
	s_barrier

;     DI bool next(int i, Unit& u) const {
;         const long L = (long)i * G + c; if (L >= nwg) return false;
;         int wgid = (int)L; { const int q = nwg / NXCD, r = nwg % NXCD, xcd = wgid % NXCD, off = wgid / NXCD; wgid = (xcd < r ? xcd * (q + 1) : r * (q + 1) + (xcd - r) * q) + off; }
;         const int nig = WGM * nN, gid = wgid / nig, fm = gid * WGM, gsz = (nM - fm) < WGM ? (nM - fm) : WGM;
;         u.pm = fm + ((wgid % nig) % gsz); u.pn = (wgid % nig) / gsz; return true;
;     }
;     DI void operator()(const AccT& acc, const Unit& u, int wr, int wc, int fr, int fq) const {
; #pragma unroll
;         for (int ai = 0; ai < 2; ++ai) {
;             f32x4 h[4][2][2];
;             float* base = H + ((size_t)u.pm * 256 + ai * 128 + wr * 64 + fr) * 1024 + u.pn * 256 + wc * 32 + 4 * fq;
; #pragma unroll
;             for (int m = 0; m < 4; ++m)
; #pragma unroll
;                 for (int bj = 0; bj < 2; ++bj)
; #pragma unroll
;                     for (int n = 0; n < 2; ++n) h[m][bj][n] = *(const f32x4*)(base + (size_t)m * 16 * 1024 + bj * 128 + n * 16);
.LBB0_3194:
	s_or_b64 exec, exec, s[4:5]
	v_mov_b32_e32 v8, v254
	s_waitcnt lgkmcnt(0)
	s_barrier
	s_cselect_b32 s100, 1, 0
	s_cmpk_gt_u32 s2, 0xbf
	s_cbranch_scc1 .Ltaild2_1_skip
	v_writelane_b32 v255, s4, 17
	v_writelane_b32 v255, s5, 18
	v_writelane_b32 v255, s6, 19
	v_writelane_b32 v255, s7, 20
	v_writelane_b32 v255, s8, 21
	v_writelane_b32 v255, s9, 22
	v_writelane_b32 v255, s10, 23
	v_writelane_b32 v255, s11, 24
	v_writelane_b32 v255, s12, 25
	v_writelane_b32 v255, s13, 26
	v_writelane_b32 v255, s14, 27
	v_writelane_b32 v255, s15, 28
	v_writelane_b32 v255, s16, 29
	v_writelane_b32 v255, s17, 30
	v_writelane_b32 v255, s18, 31
	v_writelane_b32 v255, s19, 32
	v_writelane_b32 v255, s20, 33
	v_writelane_b32 v255, s21, 34
	v_writelane_b32 v255, s22, 35
	v_writelane_b32 v255, s23, 36
	v_writelane_b32 v255, s24, 37
	v_writelane_b32 v255, s25, 38
	v_writelane_b32 v255, s26, 39
	v_writelane_b32 v255, s27, 40
	v_writelane_b32 v255, s28, 41
	v_writelane_b32 v255, s29, 42
	v_writelane_b32 v255, s30, 43
	v_writelane_b32 v255, s31, 44
	v_writelane_b32 v255, s36, 45
	v_writelane_b32 v255, s37, 46
	v_writelane_b32 v255, s38, 47
	v_writelane_b32 v255, s39, 48
	v_writelane_b32 v255, s40, 49
	v_writelane_b32 v255, s41, 50
	v_writelane_b32 v255, s42, 51
	v_writelane_b32 v255, s43, 52
	v_writelane_b32 v255, s44, 53
	v_writelane_b32 v255, s45, 54
	v_writelane_b32 v255, s46, 55
	v_writelane_b32 v255, s47, 56
	v_writelane_b32 v255, s48, 57
	v_writelane_b32 v255, s49, 58
	v_writelane_b32 v255, s50, 59
	v_writelane_b32 v255, s51, 60
	s_mov_b32 s98, m0
	s_and_b32 s4, s2, 7
	s_lshr_b32 s5, s2, 3
	s_and_b32 s6, s5, 3
	s_lshr_b32 s5, s5, 2
	s_lshl_b32 s5, s5, 3
	s_add_u32 s5, s5, s4
	s_and_b32 s7, s5, 3
	s_lshr_b32 s8, s5, 2
	s_mov_b32 s9, 0x28
	s_cmp_eq_u32 s8, 1
	s_cselect_b32 s9, 0x52, s9
	s_cmp_eq_u32 s8, 2
	s_cselect_b32 s9, 0x7c, s9
	s_cmp_eq_u32 s8, 3
	s_cselect_b32 s9, 0xa6, s9
	s_cmp_eq_u32 s8, 4
	s_cselect_b32 s9, 0x2c8, s9
	s_cmp_eq_u32 s8, 5
	s_cselect_b32 s9, 0x2f1, s9
	s_cmp_eq_u32 s8, 6
	s_cselect_b32 s9, 0x31a, s9
	s_cmp_eq_u32 s8, 7
	s_cselect_b32 s9, 0x742, s9
	s_cmp_eq_u32 s8, 8
	s_cselect_b32 s9, 0x29, s9
	s_cmp_eq_u32 s8, 9
	s_cselect_b32 s9, 0x53, s9
	s_cmp_eq_u32 s8, 10
	s_cselect_b32 s9, 0x7d, s9
	s_cmp_eq_u32 s8, 11
	s_cselect_b32 s9, 0xa7, s9
	s_and_b32 s10, s9, 0x1ff
	s_lshr_b32 s11, s9, 9
	s_lshl_b32 s12, s10, 8
	s_lshl_b32 s4, s7, 6
	s_add_u32 s12, s12, s4
	s_lshl_b32 s13, s11, 8
	s_lshl_b32 s4, s6, 6
	s_add_u32 s13, s13, s4
	s_mul_i32 s4, s12, 0x1600
	s_add_u32 s4, s4, 0x19548000
	s_add_u32 s16, s34, s4
	s_addc_u32 s17, s35, 0
	s_mul_i32 s4, s13, 0x1600
	s_add_u32 s4, s4, 0x187a0000
	s_add_u32 s18, s34, s4
	s_addc_u32 s19, s35, 0
	s_lshl_b32 s4, s12, 12
	s_lshl_b32 s5, s13, 2
	s_add_u32 s4, s4, s5
	s_add_u32 s20, s34, s4
	s_addc_u32 s21, s35, 0
	s_lshr_b32 s15, s33, 6
	s_and_b32 s27, s15, 1
	s_bfe_u32 s29, s15, 0x10001
	s_lshr_b32 s31, s15, 2
	v_and_b32_e32 v0, 31, v254
	v_lshrrev_b32_e32 v1, 5, v254
	v_mul_u32_u24_e32 v2, 0x90, v0
	v_lshl_add_u32 v2, v1, 4, v2
	s_mul_i32 s4, s27, 0x1200
	s_lshl_b32 s5, s31, 6
	s_add_u32 s4, s4, s5
	s_mul_i32 s6, s29, 0x1200
	s_add_u32 s6, s6, s5
	s_add_u32 s6, s6, 0x2400
	v_add_u32_e32 v3, s6, v2
	v_add_u32_e32 v2, s4, v2
	s_lshl_b32 s4, s27, 17
	s_lshl_b32 s5, s31, 16
	s_add_u32 s4, s4, s5
	s_lshl_b32 s5, s29, 7
	s_add_u32 s4, s4, s5
	v_lshlrev_b32_e32 v4, 14, v1
	v_lshl_add_u32 v4, v0, 2, v4
	v_add_u32_e32 v4, s4, v4
	v_mov_b32_e32 v72, v4
	v_add_u32_e32 v73, 0x1000, v4
	v_add_u32_e32 v74, 0x2000, v4
	v_add_u32_e32 v75, 0x3000, v4
	v_add_u32_e32 v76, 0x8000, v4
	v_add_u32_e32 v77, 0x9000, v4
	v_add_u32_e32 v78, 0xa000, v4
	v_add_u32_e32 v79, 0xb000, v4
	global_load_dword v64, v72, s[20:21]
	global_load_dword v65, v73, s[20:21]
	global_load_dword v66, v74, s[20:21]
	global_load_dword v67, v75, s[20:21]
	global_load_dword v68, v76, s[20:21]
	global_load_dword v69, v77, s[20:21]
	global_load_dword v70, v78, s[20:21]
	global_load_dword v71, v79, s[20:21]
	s_movk_i32 s48, 0x71c8
	s_mov_b32 s7, 0x1600
; #define PG8_STAGE(bufoff, gbase, voff) do { _Pragma("unroll") for (int _i = 0; _i < 2; ++_i) \
;         __builtin_amdgcn_global_load_lds((const unsigned*)((const char*)(gbase) + (voff)[_i]), (LAS unsigned*)(lds + (bufoff) + ldsw + _i * 8192), 16, 0, 0); } while (0)
; #define PG8_WAIT_V(n) asm volatile("s_waitcnt vmcnt(" #n ")" ::: "memory")
; #define PG8_BAR __builtin_amdgcn_s_barrier()
; template <class Epi>
; DI void gemm_phase(int wv, LAS unsigned char* lds, const Gemm g, const StaticOrder& S, const Epi& E) {
;     ...
;     for (int i = 0; i < 2; ++i) { int R, C; stage_rc(tid * 16 + i * 8192, R, C); const int Rb = Epi::PERM ? ((R & ~31) + perm32(R & 31)) : R; voffA[i] = (unsigned)(R * K + C) * 2u; voffB[i] = (unsigned)(Rb * K + C) * 2u; }
;     const size_t kstep = (size_t)(BK * 2);
;     const size_t hstep = (size_t)HALF * K * 2;
;     const size_t tstep = 2 * hstep;
;     const unsigned ldsw = (unsigned)wid * 1024u;
;     const int aoff = lds_byte(wr * 64 + fr, fq * 8), boff = lds_byte(wc * 32 + fr, fq * 8);
;     ...
;     Unit cur, nxt; int ui = 0;
;     if (!S.next(0, cur)) return;
;     f32x4 acc[2][2][4][2];
; #pragma unroll
;     for (int a = 0; a < 2; ++a)
; #pragma unroll
;         for (int b = 0; b < 2; ++b)
; #pragma unroll
;             for (int m = 0; m < 4; ++m)
; #pragma unroll
;                 for (int n = 0; n < 2; ++n) acc[a][b][m][n] = (f32x4){0.f, 0.f, 0.f, 0.f};
;     bf16x8 At[4][2], B0[2][2], B1[2][2];
;     const char* cA = (const char*)g.A + (size_t)cur.pm * tstep; const char* cB = (const char*)g.Bt + (size_t)cur.pn * tstep;
;     PG8_STAGE(PG8_SB(0, 0), cB, voffB); PG8_STAGE(PG8_SA(0, 0), cA, voffA); PG8_STAGE(PG8_SB(0, 1), cB + hstep, voffB); PG8_STAGE(PG8_SA(0, 1), cA + hstep, voffA);
;     if (wr == 1) PG8_BAR;
;     PG8_WAIT_V(4); PG8_BAR;
;     PG8_STAGE(PG8_SB(1, 0), cB + kstep, voffB); PG8_STAGE(PG8_SA(1, 0), cA + kstep, voffA); PG8_STAGE(PG8_SB(1, 1), cB + hstep + kstep, voffB);
;     PG8_WAIT_V(6); PG8_BAR;
	s_movk_i32 s36, 0x80
	s_mov_b32 s37, 0
	s_lshl_b32 s4, s15, 6
	s_mov_b64 s[42:43], s[16:17]
	s_lshl_b32 s24, s15, 10
	v_add_u32_e32 v5, s4, v254
	v_mul_lo_u32 v6, v5, s48
	v_lshrrev_b32_e32 v6, 18, v6
	v_mul_u32_u24_e32 v7, 9, v6
	v_sub_u32_e32 v5, v5, v7
	v_cmp_ne_u32_e64 s[22:23], 8, v5
	s_nop 1
	v_cndmask_b32_e64 v5, 0, v5, s[22:23]
	v_mul_lo_u32 v6, v6, s7
	v_lshl_add_u32 v10, v5, 4, v6
	v_mov_b32_e32 v11, 0
	v_lshl_add_u64 v[10:11], s[42:43], 0, v[10:11]
	s_lshl_b32 s4, s15, 6
	s_lshl_b32 s25, s15, 10
	s_movk_i32 s5, 0xffc0
	s_cmp_eq_u32 s15, 0
	s_cselect_b32 s5, 0x200, s5
	s_cselect_b32 s42, s16, s18
	s_cselect_b32 s43, s17, s19
	s_add_u32 s4, s4, s5
	s_add_u32 s25, s25, 0x2000
	v_add_u32_e32 v5, s4, v254
	v_mul_lo_u32 v6, v5, s48
	v_lshrrev_b32_e32 v6, 18, v6
	v_mul_u32_u24_e32 v7, 9, v6
	v_sub_u32_e32 v5, v5, v7
	v_cmp_ne_u32_e64 s[22:23], 8, v5
	s_nop 1
	v_cndmask_b32_e64 v5, 0, v5, s[22:23]
	v_mul_lo_u32 v6, v6, s7
	v_lshl_add_u32 v12, v5, 4, v6
	v_mov_b32_e32 v13, 0
	v_lshl_add_u64 v[12:13], s[42:43], 0, v[12:13]
	s_lshl_b32 s4, s15, 4
	s_add_u32 s4, s4, 0x1c0
	s_mov_b64 s[42:43], s[18:19]
	s_lshl_b32 s26, s15, 8
	s_add_u32 s26, s26, 0x4000
	v_add_u32_e32 v5, s4, v254
	v_mul_lo_u32 v6, v5, s48
	v_lshrrev_b32_e32 v6, 18, v6
	v_mul_u32_u24_e32 v7, 9, v6
	v_sub_u32_e32 v5, v5, v7
	v_cmp_ne_u32_e64 s[22:23], 8, v5
	s_nop 1
	v_cndmask_b32_e64 v5, 0, v5, s[22:23]
	v_mul_lo_u32 v6, v6, s7
	v_lshl_add_u32 v14, v5, 4, v6
	v_mov_b32_e32 v15, 0
	v_lshl_add_u64 v[14:15], s[42:43], 0, v[14:15]
	s_mov_b32 s28, 0x0
	s_add_u32 m0, s28, s24
	s_nop 0
	global_load_lds_dwordx4 v[10:11], off
	v_lshl_add_u64 v[10:11], v[10:11], 0, s[36:37]
	s_add_u32 m0, s28, s25
	s_nop 0
	global_load_lds_dwordx4 v[12:13], off
	v_lshl_add_u64 v[12:13], v[12:13], 0, s[36:37]
	s_add_u32 m0, s28, s26
	s_mov_b64 exec, 0xffff
	global_load_lds_dwordx4 v[14:15], off
	s_mov_b64 exec, -1
	v_lshl_add_u64 v[14:15], v[14:15], 0, s[36:37]
	s_mov_b32 s28, 0x4800
	s_add_u32 m0, s28, s24
	s_nop 0
	global_load_lds_dwordx4 v[10:11], off
	v_lshl_add_u64 v[10:11], v[10:11], 0, s[36:37]
	s_add_u32 m0, s28, s25
	s_nop 0
	global_load_lds_dwordx4 v[12:13], off
	v_lshl_add_u64 v[12:13], v[12:13], 0, s[36:37]
	s_add_u32 m0, s28, s26
	s_mov_b64 exec, 0xffff
	global_load_lds_dwordx4 v[14:15], off
	s_mov_b64 exec, -1
	v_lshl_add_u64 v[14:15], v[14:15], 0, s[36:37]
	s_mov_b32 s28, 0x9000
	s_add_u32 m0, s28, s24
	s_nop 0
	global_load_lds_dwordx4 v[10:11], off
	v_lshl_add_u64 v[10:11], v[10:11], 0, s[36:37]
	s_add_u32 m0, s28, s25
	s_nop 0
	global_load_lds_dwordx4 v[12:13], off
	v_lshl_add_u64 v[12:13], v[12:13], 0, s[36:37]
	s_add_u32 m0, s28, s26
	s_mov_b64 exec, 0xffff
	global_load_lds_dwordx4 v[14:15], off
	s_mov_b64 exec, -1
	v_lshl_add_u64 v[14:15], v[14:15], 0, s[36:37]
	s_mov_b32 s28, 0xd800
	s_add_u32 m0, s28, s24
	s_nop 0
	global_load_lds_dwordx4 v[10:11], off
	v_lshl_add_u64 v[10:11], v[10:11], 0, s[36:37]
	s_add_u32 m0, s28, s25
	s_nop 0
	global_load_lds_dwordx4 v[12:13], off
	v_lshl_add_u64 v[12:13], v[12:13], 0, s[36:37]
	s_add_u32 m0, s28, s26
	s_mov_b64 exec, 0xffff
	global_load_lds_dwordx4 v[14:15], off
	s_mov_b64 exec, -1
	v_lshl_add_u64 v[14:15], v[14:15], 0, s[36:37]
	s_mov_b32 s28, 0x12000
	s_add_u32 m0, s28, s24
	s_nop 0
	global_load_lds_dwordx4 v[10:11], off
	v_lshl_add_u64 v[10:11], v[10:11], 0, s[36:37]
	s_add_u32 m0, s28, s25
	s_nop 0
	global_load_lds_dwordx4 v[12:13], off
	v_lshl_add_u64 v[12:13], v[12:13], 0, s[36:37]
	s_add_u32 m0, s28, s26
	s_mov_b64 exec, 0xffff
	global_load_lds_dwordx4 v[14:15], off
	s_mov_b64 exec, -1
	v_lshl_add_u64 v[14:15], v[14:15], 0, s[36:37]
	v_mov_b32_e32 v32, 0
	v_mov_b32_e32 v33, 0
	v_mov_b32_e32 v34, 0
	v_mov_b32_e32 v35, 0
	v_mov_b32_e32 v36, 0
	v_mov_b32_e32 v37, 0
	v_mov_b32_e32 v38, 0
	v_mov_b32_e32 v39, 0
	v_mov_b32_e32 v40, 0
	v_mov_b32_e32 v41, 0
	v_mov_b32_e32 v42, 0
	v_mov_b32_e32 v43, 0
	v_mov_b32_e32 v44, 0
	v_mov_b32_e32 v45, 0
	v_mov_b32_e32 v46, 0
	v_mov_b32_e32 v47, 0
	s_mov_b32 s28, 0x16800
	s_mov_b32 s30, 0
	s_mov_b32 s14, 0

;     DI bool next(int i, Unit& u) const {
;         const long L = (long)i * G + c; if (L >= nwg) return false;
;         int wgid = (int)L; { const int q = nwg / NXCD, r = nwg % NXCD, xcd = wgid % NXCD, off = wgid / NXCD; wgid = (xcd < r ? xcd * (q + 1) : r * (q + 1) + (xcd - r) * q) + off; }
;         const int nig = WGM * nN, gid = wgid / nig, fm = gid * WGM, gsz = (nM - fm) < WGM ? (nM - fm) : WGM;
;         u.pm = fm + ((wgid % nig) % gsz); u.pn = (wgid % nig) / gsz; return true;
;     }
; template <class Epi>
; DI void gemm_phase(int wv, LAS unsigned char* lds, const Gemm g, const StaticOrder& S, const Epi& E) {
;     ...
;     if (!S.next(0, cur)) return;
.Ltaild2_1_skip:
	s_cmp_lg_u32 s100, 0
	s_and_b64 vcc, exec, s[6:7]
	v_add_u32_e32 v0, s33, v8
	s_nop 0
	v_readfirstlane_b32 s26, v0
	s_cbranch_vccnz .LBB0_3218
	s_lshr_b32 s4, s3, 29
	s_add_i32 s7, s2, s4
	s_and_b32 s4, s7, -8
	s_sub_i32 s6, s2, s4
	s_cmp_gt_i32 s6, 3
	s_cbranch_scc0 .LBB0_3197
	s_mul_i32 s4, s6, 0xa1
	s_add_i32 s8, s4, 4
	s_ashr_i32 s4, s7, 3
	s_cbranch_execz .LBB0_3198
	s_branch .LBB0_3199

; #define PG8_STAGE(bufoff, gbase, voff) do { _Pragma("unroll") for (int _i = 0; _i < 2; ++_i) \
;         __builtin_amdgcn_global_load_lds((const unsigned*)((const char*)(gbase) + (voff)[_i]), (LAS unsigned*)(lds + (bufoff) + ldsw + _i * 8192), 16, 0, 0); } while (0)
; #define PG8_WAIT_V(n) asm volatile("s_waitcnt vmcnt(" #n ")" ::: "memory")
; #define PG8_BAR __builtin_amdgcn_s_barrier()
;     DI bool next(int i, Unit& u) const {
;         const long L = (long)i * G + c; if (L >= nwg) return false;
;         int wgid = (int)L; { const int q = nwg / NXCD, r = nwg % NXCD, xcd = wgid % NXCD, off = wgid / NXCD; wgid = (xcd < r ? xcd * (q + 1) : r * (q + 1) + (xcd - r) * q) + off; }
; template <class Epi>
; DI void gemm_phase(int wv, LAS unsigned char* lds, const Gemm g, const StaticOrder& S, const Epi& E) {
;     ...
;     for (int i = 0; i < 2; ++i) { int R, C; stage_rc(tid * 16 + i * 8192, R, C); const int Rb = Epi::PERM ? ((R & ~31) + perm32(R & 31)) : R; voffA[i] = (unsigned)(R * K + C) * 2u; voffB[i] = (unsigned)(Rb * K + C) * 2u; }
;     const size_t kstep = (size_t)(BK * 2);
;     const size_t hstep = (size_t)HALF * K * 2;
;     const size_t tstep = 2 * hstep;
;     const unsigned ldsw = (unsigned)wid * 1024u;
;     const int aoff = lds_byte(wr * 64 + fr, fq * 8), boff = lds_byte(wc * 32 + fr, fq * 8);
;     ...
;     Unit cur, nxt; int ui = 0;
;     if (!S.next(0, cur)) return;
;     f32x4 acc[2][2][4][2];
; #pragma unroll
;     for (int a = 0; a < 2; ++a)
; #pragma unroll
;         for (int b = 0; b < 2; ++b)
; #pragma unroll
;             for (int m = 0; m < 4; ++m)
; #pragma unroll
;                 for (int n = 0; n < 2; ++n) acc[a][b][m][n] = (f32x4){0.f, 0.f, 0.f, 0.f};
;     bf16x8 At[4][2], B0[2][2], B1[2][2];
;     const char* cA = (const char*)g.A + (size_t)cur.pm * tstep; const char* cB = (const char*)g.Bt + (size_t)cur.pn * tstep;
;     PG8_STAGE(PG8_SB(0, 0), cB, voffB); PG8_STAGE(PG8_SA(0, 0), cA, voffA); PG8_STAGE(PG8_SB(0, 1), cB + hstep, voffB); PG8_STAGE(PG8_SA(0, 1), cA + hstep, voffA);
;     if (wr == 1) PG8_BAR;
;     PG8_WAIT_V(4); PG8_BAR;
;     PG8_STAGE(PG8_SB(1, 0), cB + kstep, voffB); PG8_STAGE(PG8_SA(1, 0), cA + kstep, voffA); PG8_STAGE(PG8_SB(1, 1), cB + hstep + kstep, voffB);
;     PG8_WAIT_V(6); PG8_BAR;
.LBB0_3201:
	s_lshl_b32 s8, s6, 6
	s_lshl_b32 s9, s6, 13
	s_lshl_b32 s6, s7, 5
	s_mov_b64 s[12:13], 0x80
	s_and_b32 s10, s6, 0x60
	s_add_i32 m0, s30, 0x18000
	v_lshl_add_u64 v[6:7], v[6:7], 0, s[12:13]
	s_lshl_b32 s14, s10, 7
	s_waitcnt vmcnt(4)
	s_barrier
	global_load_lds_dwordx4 v[6:7], off
	v_lshl_add_u64 v[4:5], v[4:5], 0, s[12:13]
	s_add_i32 m0, s30, 0x1a000
	s_add_i32 s46, s30, 0x8000
	s_add_i32 s47, s30, 0xa000
	global_load_lds_dwordx4 v[4:5], off
	v_lshl_add_u64 v[2:3], v[2:3], 0, s[12:13]
	s_mov_b32 m0, s46
	s_add_u32 s6, s20, 0xb0080
	global_load_lds_dwordx4 v[2:3], off
	v_lshl_add_u64 v[0:1], v[0:1], 0, s[12:13]
	s_mov_b32 m0, s47
	s_addc_u32 s7, s21, 0
	global_load_lds_dwordx4 v[0:1], off
	s_add_i32 m0, s30, 0x1c000
	v_lshl_add_u64 v[0:1], s[6:7], 0, v[128:129]
	global_load_lds_dwordx4 v[0:1], off
	v_lshl_add_u64 v[0:1], s[6:7], 0, v[130:131]
	s_add_i32 m0, s30, 0x1e000
	v_bfe_u32 v2, v8, 4, 2
	global_load_lds_dwordx4 v[0:1], off
	v_and_b32_e32 v0, 15, v8
	v_lshlrev_b32_e32 v1, 4, v2
	v_lshlrev_b32_e32 v3, 2, v8
	s_sext_i32_i8 s59, s4
	v_lshl_or_b32 v1, v0, 6, v1
	v_and_b32_e32 v3, 32, v3
	s_ashr_i32 s4, s8, 31
	v_bitop3_b32 v4, v1, s9, v3 bitop3:0xde
	v_bitop3_b32 v146, v1, s14, v3 bitop3:0xde
	v_or_b32_e32 v0, s8, v0
	v_mov_b32_e32 v1, s4
	v_lshlrev_b64 v[0:1], 12, v[0:1]
	v_lshl_add_u64 v[134:135], s[22:23], 0, v[0:1]
	v_lshrrev_b32_e32 v1, 1, v9
	v_mul_lo_u32 v0, v11, s5
	s_mov_b32 s4, 0xb000
	v_mad_u64_u32 v[0:1], s[8:9], v1, s4, v[0:1]
	v_or_b32_e32 v0, v0, v10
	v_add_lshl_u32 v132, v0, v12, 1
	v_lshrrev_b32_e32 v1, 1, v13
	v_mul_lo_u32 v0, v14, s5
	v_mad_u64_u32 v[0:1], s[4:5], v1, s4, v[0:1]
	s_mov_b64 s[6:7], 0xb0080
	s_waitcnt vmcnt(6)
	v_or_b32_e32 v0, v0, v15
	v_lshlrev_b32_e32 v2, 2, v2
	v_lshl_add_u64 v[136:137], v[132:133], 0, s[6:7]
	v_add_lshl_u32 v132, v0, v16, 1
	s_add_i32 s48, 0, 0x10000
	s_add_i32 s49, 0, 0x14000
	v_lshl_add_u64 v[138:139], v[132:133], 0, s[6:7]
	v_mov_b64_e32 v[140:141], 0x500
	v_mov_b64_e32 v[142:143], 0x4ff
	v_add_u32_e32 v147, s48, v146
	v_add_u32_e32 v148, 0, v4
	v_add_u32_e32 v149, s49, v146
	s_lshl_b32 s10, s10, 2
	v_lshlrev_b32_e32 v132, 2, v2
	s_mov_b32 s50, 0x20000
	s_mov_b32 s51, 0x30000
	s_mov_b64 s[14:15], 0x80000
	s_mov_b32 s52, 0x80000
	s_mov_b32 s53, 0x90000
	s_mov_b32 s54, 0xa0000
	s_mov_b32 s55, 0xb0000
	s_mov_b32 s56, s11
	s_barrier
